# fused OUT/DOWN epilogues: row-stat reductions across 16-lane rows by permlane swaps instead of ds_bpermute
# baseline (speedup 1.0000x reference)
.LBB0_632:
	v_mul_f32_e32 v151, v125, v125
	v_mul_f32_e32 v154, v127, v127
	v_fmac_f32_e32 v151, v124, v124
	v_fmac_f32_e32 v154, v126, v126
	v_add_f32_e32 v151, v151, v154
	v_mul_f32_e32 v154, v121, v121
	v_fmac_f32_e32 v154, v120, v120
	v_cvt_pk_bf16_f32 v124, v124, v125
	v_cvt_pk_bf16_f32 v125, v126, v127
	v_cvt_pk_bf16_f32 v126, v120, v121
	v_mul_f32_e32 v120, v117, v117
	v_mul_f32_e32 v121, v119, v119
	v_fmac_f32_e32 v120, v116, v116
	v_fmac_f32_e32 v121, v118, v118
	v_add_f32_e32 v120, v120, v121
	v_mul_f32_e32 v121, v113, v113
	v_fmac_f32_e32 v121, v112, v112
	v_add_f32_e32 v151, v151, v154
	v_mul_f32_e32 v154, v123, v123
	v_add_f32_e32 v120, v120, v121
	v_mul_f32_e32 v121, v115, v115
	v_fmac_f32_e32 v154, v122, v122
	v_fmac_f32_e32 v121, v114, v114
	v_add_f32_e32 v151, v154, v151
	v_add_f32_e32 v120, v121, v120
	v_lshl_add_u32 v144, s10, 8, v146
	v_add_f32_e32 v120, v151, v120
	v_ashrrev_i32_e32 v145, 31, v144
	v_mov_b32_e32 v121, v120
	s_nop 1
	v_permlane16_swap_b32 v120, v121
	v_lshlrev_b64 v[142:143], 11, v[144:145]
	s_lshl_b32 s6, s14, 8
	v_lshl_add_u64 v[142:143], s[20:21], 0, v[142:143]
	s_ashr_i32 s7, s6, 31
	v_lshl_add_u64 v[142:143], s[6:7], 1, v[142:143]
	s_mov_b32 s69, s45
	v_lshl_add_u64 v[142:143], v[142:143], 0, s[68:69]
	v_lshl_add_u64 v[142:143], v[142:143], 0, v[136:137]
	v_cvt_pk_bf16_f32 v127, v122, v123
	s_mov_b64 s[6:7], 0x100
	global_store_dwordx4 v[142:143], v[124:127], off sc0 sc1
	s_nop 1
	v_cvt_pk_bf16_f32 v116, v116, v117
	v_cvt_pk_bf16_f32 v117, v118, v119
	v_cvt_pk_bf16_f32 v118, v112, v113
	v_cvt_pk_bf16_f32 v119, v114, v115
	s_waitcnt lgkmcnt(0)
	v_add_f32_e32 v114, v120, v121
	v_mov_b32_e32 v115, v114
	s_nop 1
	v_permlane32_swap_b32 v114, v115
	v_lshl_add_u64 v[112:113], v[142:143], 0, s[6:7]
	global_store_dwordx4 v[112:113], v[116:119], off sc0 sc1
	s_nop 1
	v_readlane_b32 s6, v254, 60
	v_lshlrev_b64 v[112:113], 2, v[144:145]
	v_readlane_b32 s7, v254, 61
	s_nop 1
	v_lshl_add_u64 v[112:113], s[6:7], 0, v[112:113]
	s_and_saveexec_b64 s[6:7], s[0:1]
	s_cbranch_execz .LBB0_634
	s_mul_i32 s18, s14, 0x43000
	s_ashr_i32 s19, s18, 31
	s_waitcnt lgkmcnt(0)
	v_add_f32_e32 v116, v114, v115
	v_lshl_add_u64 v[114:115], s[18:19], 0, v[112:113]
	s_mul_i32 s44, s33, 0x10c00
	v_lshl_add_u64 v[114:115], v[114:115], 0, s[44:45]
	global_store_dword v[114:115], v116, off sc0 sc1
	s_nop 1
.LBB0_634:
	s_or_b64 exec, exec, s[6:7]
	v_mul_f32_e32 v116, v109, v109
	v_mul_f32_e32 v117, v111, v111
	v_fmac_f32_e32 v116, v108, v108
	v_fmac_f32_e32 v117, v110, v110
	v_add_f32_e32 v116, v116, v117
	v_mul_f32_e32 v117, v105, v105
	v_fmac_f32_e32 v117, v104, v104
	v_cvt_pk_bf16_f32 v108, v108, v109
	v_cvt_pk_bf16_f32 v109, v110, v111
	v_cvt_pk_bf16_f32 v110, v104, v105
	v_mul_f32_e32 v104, v101, v101
	v_mul_f32_e32 v105, v103, v103
	v_fmac_f32_e32 v104, v100, v100
	v_fmac_f32_e32 v105, v102, v102
	v_add_f32_e32 v104, v104, v105
	v_mul_f32_e32 v105, v97, v97
	v_fmac_f32_e32 v105, v96, v96
	v_add_f32_e32 v116, v116, v117
	v_mul_f32_e32 v117, v107, v107
	v_add_f32_e32 v104, v104, v105
	v_mul_f32_e32 v105, v99, v99
	v_fmac_f32_e32 v117, v106, v106
	v_fmac_f32_e32 v105, v98, v98
	v_add_f32_e32 v116, v117, v116
	v_add_f32_e32 v104, v105, v104
	v_add_f32_e32 v104, v116, v104
	v_mov_b32_e32 v105, v104
	s_nop 1
	v_permlane16_swap_b32 v104, v105
	s_mov_b64 s[6:7], 0x8000
	s_waitcnt lgkmcnt(0)
	v_lshl_add_u64 v[114:115], v[142:143], 0, s[6:7]
	v_cvt_pk_bf16_f32 v111, v106, v107
	s_mov_b64 s[6:7], 0x8100
	global_store_dwordx4 v[114:115], v[108:111], off sc0 sc1
	s_nop 1
	v_cvt_pk_bf16_f32 v100, v100, v101
	v_cvt_pk_bf16_f32 v101, v102, v103
	v_cvt_pk_bf16_f32 v102, v96, v97
	v_add_f32_e32 v96, v104, v105
	v_mov_b32_e32 v97, v96
	s_nop 1
	v_permlane32_swap_b32 v96, v97
	v_cvt_pk_bf16_f32 v103, v98, v99
	v_lshl_add_u64 v[98:99], v[142:143], 0, s[6:7]
	global_store_dwordx4 v[98:99], v[100:103], off sc0 sc1
	s_nop 1
	s_and_saveexec_b64 s[6:7], s[0:1]
	s_cbranch_execz .LBB0_636
	s_waitcnt lgkmcnt(0)
	v_add_f32_e32 v98, v96, v97
	v_or_b32_e32 v96, 16, v144
	v_ashrrev_i32_e32 v97, 31, v96
	v_readlane_b32 s12, v254, 60
	v_lshlrev_b64 v[96:97], 2, v[96:97]
	v_readlane_b32 s13, v254, 61
	s_mul_i32 s18, s14, 0x43000
	s_ashr_i32 s19, s18, 31
	v_lshl_add_u64 v[96:97], s[12:13], 0, v[96:97]
	v_lshl_add_u64 v[96:97], s[18:19], 0, v[96:97]
	s_mul_i32 s44, s33, 0x10c00
	v_lshl_add_u64 v[96:97], v[96:97], 0, s[44:45]
	global_store_dword v[96:97], v98, off sc0 sc1
	s_nop 1
.LBB0_636:
	s_or_b64 exec, exec, s[6:7]
	v_mul_f32_e32 v98, v93, v93
	v_mul_f32_e32 v99, v95, v95
	v_fmac_f32_e32 v98, v92, v92
	v_fmac_f32_e32 v99, v94, v94
	v_add_f32_e32 v98, v98, v99
	v_mul_f32_e32 v99, v89, v89
	v_fmac_f32_e32 v99, v88, v88
	v_cvt_pk_bf16_f32 v92, v92, v93
	v_cvt_pk_bf16_f32 v93, v94, v95
	v_cvt_pk_bf16_f32 v94, v88, v89
	v_mul_f32_e32 v88, v85, v85
	v_mul_f32_e32 v89, v87, v87
	v_fmac_f32_e32 v88, v84, v84
	v_fmac_f32_e32 v89, v86, v86
	v_add_f32_e32 v88, v88, v89
	v_mul_f32_e32 v89, v81, v81
	v_fmac_f32_e32 v89, v80, v80
	v_add_f32_e32 v98, v98, v99
	v_mul_f32_e32 v99, v91, v91
	v_add_f32_e32 v88, v88, v89
	v_mul_f32_e32 v89, v83, v83
	v_fmac_f32_e32 v99, v90, v90
	v_fmac_f32_e32 v89, v82, v82
	v_add_f32_e32 v98, v99, v98
	v_add_f32_e32 v88, v89, v88
	v_add_f32_e32 v88, v98, v88
	v_mov_b32_e32 v89, v88
	s_nop 1
	v_permlane16_swap_b32 v88, v89
	s_mov_b64 s[6:7], 0x10000
	s_waitcnt lgkmcnt(0)
	v_lshl_add_u64 v[96:97], v[142:143], 0, s[6:7]
	v_cvt_pk_bf16_f32 v95, v90, v91
	s_mov_b64 s[6:7], 0x10100
	global_store_dwordx4 v[96:97], v[92:95], off sc0 sc1
	s_nop 1
	v_cvt_pk_bf16_f32 v84, v84, v85
	v_cvt_pk_bf16_f32 v85, v86, v87
	v_cvt_pk_bf16_f32 v86, v80, v81
	v_add_f32_e32 v80, v88, v89
	v_mov_b32_e32 v81, v80
	s_nop 1
	v_permlane32_swap_b32 v80, v81
	v_cvt_pk_bf16_f32 v87, v82, v83
	v_lshl_add_u64 v[82:83], v[142:143], 0, s[6:7]
	global_store_dwordx4 v[82:83], v[84:87], off sc0 sc1
	s_nop 1
	s_and_saveexec_b64 s[6:7], s[0:1]
	s_cbranch_execz .LBB0_638
	s_waitcnt lgkmcnt(0)
	v_add_f32_e32 v82, v80, v81
	v_or_b32_e32 v80, 32, v144
	v_ashrrev_i32_e32 v81, 31, v80
	v_readlane_b32 s12, v254, 60
	v_lshlrev_b64 v[80:81], 2, v[80:81]
	v_readlane_b32 s13, v254, 61
	s_mul_i32 s18, s14, 0x43000
	s_ashr_i32 s19, s18, 31
	v_lshl_add_u64 v[80:81], s[12:13], 0, v[80:81]
	v_lshl_add_u64 v[80:81], s[18:19], 0, v[80:81]
	s_mul_i32 s44, s33, 0x10c00
	v_lshl_add_u64 v[80:81], v[80:81], 0, s[44:45]
	global_store_dword v[80:81], v82, off sc0 sc1
	s_nop 1
.LBB0_638:
	s_or_b64 exec, exec, s[6:7]
	v_mul_f32_e32 v82, v77, v77
	v_mul_f32_e32 v83, v79, v79
	v_fmac_f32_e32 v82, v76, v76
	v_fmac_f32_e32 v83, v78, v78
	v_add_f32_e32 v82, v82, v83
	v_mul_f32_e32 v83, v73, v73
	v_fmac_f32_e32 v83, v72, v72
	v_cvt_pk_bf16_f32 v76, v76, v77
	v_cvt_pk_bf16_f32 v77, v78, v79
	v_cvt_pk_bf16_f32 v78, v72, v73
	v_mul_f32_e32 v72, v69, v69
	v_mul_f32_e32 v73, v71, v71
	v_fmac_f32_e32 v72, v68, v68
	v_fmac_f32_e32 v73, v70, v70
	v_add_f32_e32 v72, v72, v73
	v_mul_f32_e32 v73, v65, v65
	v_fmac_f32_e32 v73, v64, v64
	v_add_f32_e32 v82, v82, v83
	v_mul_f32_e32 v83, v75, v75
	v_add_f32_e32 v72, v72, v73
	v_mul_f32_e32 v73, v67, v67
	v_fmac_f32_e32 v83, v74, v74
	v_fmac_f32_e32 v73, v66, v66
	v_add_f32_e32 v82, v83, v82
	v_add_f32_e32 v72, v73, v72
	v_add_f32_e32 v72, v82, v72
	v_mov_b32_e32 v73, v72
	s_nop 1
	v_permlane16_swap_b32 v72, v73
	s_mov_b64 s[6:7], 0x18000
	s_waitcnt lgkmcnt(0)
	v_lshl_add_u64 v[80:81], v[142:143], 0, s[6:7]
	v_cvt_pk_bf16_f32 v79, v74, v75
	s_mov_b64 s[6:7], 0x18100
	global_store_dwordx4 v[80:81], v[76:79], off sc0 sc1
	s_nop 1
	v_cvt_pk_bf16_f32 v68, v68, v69
	v_cvt_pk_bf16_f32 v69, v70, v71
	v_cvt_pk_bf16_f32 v70, v64, v65
	v_add_f32_e32 v64, v72, v73
	v_mov_b32_e32 v65, v64
	s_nop 1
	v_permlane32_swap_b32 v64, v65
	v_cvt_pk_bf16_f32 v71, v66, v67
	v_lshl_add_u64 v[66:67], v[142:143], 0, s[6:7]
	global_store_dwordx4 v[66:67], v[68:71], off sc0 sc1
	s_nop 1
	s_and_saveexec_b64 s[6:7], s[0:1]
	s_cbranch_execz .LBB0_640
	s_waitcnt lgkmcnt(0)
	v_add_f32_e32 v66, v64, v65
	v_or_b32_e32 v64, 48, v144
	v_ashrrev_i32_e32 v65, 31, v64
	v_readlane_b32 s12, v254, 60
	v_lshlrev_b64 v[64:65], 2, v[64:65]
	v_readlane_b32 s13, v254, 61
	s_mul_i32 s18, s14, 0x43000
	s_ashr_i32 s19, s18, 31
	v_lshl_add_u64 v[64:65], s[12:13], 0, v[64:65]
	v_lshl_add_u64 v[64:65], s[18:19], 0, v[64:65]
	s_mul_i32 s44, s33, 0x10c00
	v_lshl_add_u64 v[64:65], v[64:65], 0, s[44:45]
	global_store_dword v[64:65], v66, off sc0 sc1
	s_nop 1
.LBB0_640:
	s_or_b64 exec, exec, s[6:7]
	v_mul_f32_e32 v66, v61, v61
	v_mul_f32_e32 v67, v63, v63
	v_fmac_f32_e32 v66, v60, v60
	v_fmac_f32_e32 v67, v62, v62
	v_add_f32_e32 v66, v66, v67
	v_mul_f32_e32 v67, v57, v57
	v_fmac_f32_e32 v67, v56, v56
	v_cvt_pk_bf16_f32 v60, v60, v61
	v_cvt_pk_bf16_f32 v61, v62, v63
	v_cvt_pk_bf16_f32 v62, v56, v57
	v_mul_f32_e32 v56, v53, v53
	v_mul_f32_e32 v57, v55, v55
	v_fmac_f32_e32 v56, v52, v52
	v_fmac_f32_e32 v57, v54, v54
	v_add_f32_e32 v56, v56, v57
	v_mul_f32_e32 v57, v49, v49
	v_fmac_f32_e32 v57, v48, v48
	v_add_f32_e32 v66, v66, v67
	v_mul_f32_e32 v67, v59, v59
	v_add_f32_e32 v56, v56, v57
	v_mul_f32_e32 v57, v51, v51
	v_fmac_f32_e32 v67, v58, v58
	v_fmac_f32_e32 v57, v50, v50
	v_add_f32_e32 v66, v67, v66
	v_add_f32_e32 v56, v57, v56
	v_add_f32_e32 v56, v66, v56
	v_mov_b32_e32 v57, v56
	s_nop 1
	v_permlane16_swap_b32 v56, v57
	s_mov_b64 s[6:7], 0x40000
	s_waitcnt lgkmcnt(0)
	v_lshl_add_u64 v[64:65], v[142:143], 0, s[6:7]
	v_cvt_pk_bf16_f32 v63, v58, v59
	s_mov_b64 s[6:7], 0x40100
	global_store_dwordx4 v[64:65], v[60:63], off sc0 sc1
	s_nop 1
	v_cvt_pk_bf16_f32 v52, v52, v53
	v_cvt_pk_bf16_f32 v53, v54, v55
	v_cvt_pk_bf16_f32 v54, v48, v49
	v_add_f32_e32 v48, v56, v57
	v_mov_b32_e32 v49, v48
	s_nop 1
	v_permlane32_swap_b32 v48, v49
	v_cvt_pk_bf16_f32 v55, v50, v51
	v_lshl_add_u64 v[50:51], v[142:143], 0, s[6:7]
	global_store_dwordx4 v[50:51], v[52:55], off sc0 sc1
	s_nop 1
	s_and_saveexec_b64 s[6:7], s[0:1]
	s_cbranch_execz .LBB0_642
	s_mul_i32 s18, s14, 0x43000
	s_ashr_i32 s19, s18, 31
	s_waitcnt lgkmcnt(0)
	v_add_f32_e32 v50, v48, v49
	v_lshl_add_u64 v[48:49], s[18:19], 0, v[112:113]
	s_mul_i32 s44, s33, 0x10c00
	v_lshl_add_u64 v[48:49], v[48:49], 0, s[44:45]
	s_mov_b64 s[18:19], 0x200
	v_lshl_add_u64 v[48:49], v[48:49], 0, s[18:19]
	global_store_dword v[48:49], v50, off sc0 sc1
	s_nop 1
.LBB0_642:
	s_or_b64 exec, exec, s[6:7]
	v_mul_f32_e32 v50, v45, v45
	v_mul_f32_e32 v51, v47, v47
	v_fmac_f32_e32 v50, v44, v44
	v_fmac_f32_e32 v51, v46, v46
	v_add_f32_e32 v50, v50, v51
	v_mul_f32_e32 v51, v41, v41
	v_fmac_f32_e32 v51, v40, v40
	v_cvt_pk_bf16_f32 v44, v44, v45
	v_cvt_pk_bf16_f32 v45, v46, v47
	v_cvt_pk_bf16_f32 v46, v40, v41
	v_mul_f32_e32 v40, v37, v37
	v_mul_f32_e32 v41, v39, v39
	v_fmac_f32_e32 v40, v36, v36
	v_fmac_f32_e32 v41, v38, v38
	v_add_f32_e32 v40, v40, v41
	v_mul_f32_e32 v41, v33, v33
	v_fmac_f32_e32 v41, v32, v32
	v_add_f32_e32 v50, v50, v51
	v_mul_f32_e32 v51, v43, v43
	v_add_f32_e32 v40, v40, v41
	v_mul_f32_e32 v41, v35, v35
	v_fmac_f32_e32 v51, v42, v42
	v_fmac_f32_e32 v41, v34, v34
	v_add_f32_e32 v50, v51, v50
	v_add_f32_e32 v40, v41, v40
	v_add_f32_e32 v40, v50, v40
	v_mov_b32_e32 v41, v40
	s_nop 1
	v_permlane16_swap_b32 v40, v41
	s_mov_b64 s[6:7], 0x48000
	s_waitcnt lgkmcnt(0)
	v_lshl_add_u64 v[48:49], v[142:143], 0, s[6:7]
	v_cvt_pk_bf16_f32 v47, v42, v43
	s_mov_b64 s[6:7], 0x48100
	global_store_dwordx4 v[48:49], v[44:47], off sc0 sc1
	s_nop 1
	v_cvt_pk_bf16_f32 v36, v36, v37
	v_cvt_pk_bf16_f32 v37, v38, v39
	v_cvt_pk_bf16_f32 v38, v32, v33
	v_add_f32_e32 v32, v40, v41
	v_mov_b32_e32 v33, v32
	s_nop 1
	v_permlane32_swap_b32 v32, v33
	v_cvt_pk_bf16_f32 v39, v34, v35
	v_lshl_add_u64 v[34:35], v[142:143], 0, s[6:7]
	global_store_dwordx4 v[34:35], v[36:39], off sc0 sc1
	s_nop 1
	s_and_saveexec_b64 s[6:7], s[0:1]
	s_cbranch_execz .LBB0_644
	s_mul_i32 s18, s14, 0x43000
	s_ashr_i32 s19, s18, 31
	s_waitcnt lgkmcnt(0)
	v_add_f32_e32 v34, v32, v33
	v_lshl_add_u64 v[32:33], s[18:19], 0, v[112:113]
	s_mul_i32 s44, s33, 0x10c00
	v_lshl_add_u64 v[32:33], v[32:33], 0, s[44:45]
	s_mov_b64 s[18:19], 0x240
	v_lshl_add_u64 v[32:33], v[32:33], 0, s[18:19]
	global_store_dword v[32:33], v34, off sc0 sc1
	s_nop 1
.LBB0_644:
	s_or_b64 exec, exec, s[6:7]
	v_mul_f32_e32 v34, v29, v29
	v_mul_f32_e32 v35, v31, v31
	v_fmac_f32_e32 v34, v28, v28
	v_fmac_f32_e32 v35, v30, v30
	v_add_f32_e32 v34, v34, v35
	v_mul_f32_e32 v35, v25, v25
	v_fmac_f32_e32 v35, v24, v24
	v_cvt_pk_bf16_f32 v28, v28, v29
	v_cvt_pk_bf16_f32 v29, v30, v31
	v_cvt_pk_bf16_f32 v30, v24, v25
	v_mul_f32_e32 v24, v21, v21
	v_mul_f32_e32 v25, v23, v23
	v_fmac_f32_e32 v24, v20, v20
	v_fmac_f32_e32 v25, v22, v22
	v_add_f32_e32 v24, v24, v25
	v_mul_f32_e32 v25, v17, v17
	v_fmac_f32_e32 v25, v16, v16
	v_add_f32_e32 v34, v34, v35
	v_mul_f32_e32 v35, v27, v27
	v_add_f32_e32 v24, v24, v25
	v_mul_f32_e32 v25, v19, v19
	v_fmac_f32_e32 v35, v26, v26
	v_fmac_f32_e32 v25, v18, v18
	v_add_f32_e32 v34, v35, v34
	v_add_f32_e32 v24, v25, v24
	v_add_f32_e32 v24, v34, v24
	v_mov_b32_e32 v25, v24
	s_nop 1
	v_permlane16_swap_b32 v24, v25
	s_mov_b64 s[6:7], 0x50000
	s_waitcnt lgkmcnt(0)
	v_lshl_add_u64 v[32:33], v[142:143], 0, s[6:7]
	v_cvt_pk_bf16_f32 v31, v26, v27
	s_mov_b64 s[6:7], 0x50100
	global_store_dwordx4 v[32:33], v[28:31], off sc0 sc1
	s_nop 1
	v_cvt_pk_bf16_f32 v20, v20, v21
	v_cvt_pk_bf16_f32 v21, v22, v23
	v_cvt_pk_bf16_f32 v22, v16, v17
	v_add_f32_e32 v16, v24, v25
	v_mov_b32_e32 v17, v16
	s_nop 1
	v_permlane32_swap_b32 v16, v17
	v_cvt_pk_bf16_f32 v23, v18, v19
	v_lshl_add_u64 v[18:19], v[142:143], 0, s[6:7]
	global_store_dwordx4 v[18:19], v[20:23], off sc0 sc1
	s_nop 1
	s_and_saveexec_b64 s[6:7], s[0:1]
	s_cbranch_execz .LBB0_646
	s_mul_i32 s18, s14, 0x43000
	s_ashr_i32 s19, s18, 31
	s_waitcnt lgkmcnt(0)
	v_add_f32_e32 v18, v16, v17
	v_lshl_add_u64 v[16:17], s[18:19], 0, v[112:113]
	s_mul_i32 s44, s33, 0x10c00
	v_lshl_add_u64 v[16:17], v[16:17], 0, s[44:45]
	s_mov_b64 s[18:19], 0x280
	v_lshl_add_u64 v[16:17], v[16:17], 0, s[18:19]
	global_store_dword v[16:17], v18, off sc0 sc1
	s_nop 1
.LBB0_646:
	s_or_b64 exec, exec, s[6:7]
	v_mul_f32_e32 v18, v13, v13
	v_mul_f32_e32 v19, v15, v15
	v_fmac_f32_e32 v18, v12, v12
	v_fmac_f32_e32 v19, v14, v14
	v_add_f32_e32 v18, v18, v19
	v_mul_f32_e32 v19, v9, v9
	v_fmac_f32_e32 v19, v8, v8
	v_cvt_pk_bf16_f32 v12, v12, v13
	v_cvt_pk_bf16_f32 v13, v14, v15
	v_cvt_pk_bf16_f32 v14, v8, v9
	v_mul_f32_e32 v8, v5, v5
	v_mul_f32_e32 v9, v7, v7
	v_fmac_f32_e32 v8, v4, v4
	v_fmac_f32_e32 v9, v6, v6
	v_add_f32_e32 v8, v8, v9
	v_mul_f32_e32 v9, v1, v1
	v_fmac_f32_e32 v9, v0, v0
	v_add_f32_e32 v18, v18, v19
	v_mul_f32_e32 v19, v11, v11
	v_add_f32_e32 v8, v8, v9
	v_mul_f32_e32 v9, v3, v3
	v_fmac_f32_e32 v19, v10, v10
	v_fmac_f32_e32 v9, v2, v2
	v_add_f32_e32 v18, v19, v18
	v_add_f32_e32 v8, v9, v8
	v_add_f32_e32 v8, v18, v8
	v_mov_b32_e32 v9, v8
	s_nop 1
	v_permlane16_swap_b32 v8, v9
	s_mov_b64 s[6:7], 0x58000
	s_waitcnt lgkmcnt(0)
	v_lshl_add_u64 v[16:17], v[142:143], 0, s[6:7]
	v_cvt_pk_bf16_f32 v15, v10, v11
	s_mov_b64 s[6:7], 0x58100
	global_store_dwordx4 v[16:17], v[12:15], off sc0 sc1
	s_nop 1
	v_cvt_pk_bf16_f32 v4, v4, v5
	v_cvt_pk_bf16_f32 v5, v6, v7
	v_cvt_pk_bf16_f32 v6, v0, v1
	v_add_f32_e32 v0, v8, v9
	v_mov_b32_e32 v1, v0
	s_nop 1
	v_permlane32_swap_b32 v0, v1
	v_cvt_pk_bf16_f32 v7, v2, v3
	v_lshl_add_u64 v[2:3], v[142:143], 0, s[6:7]
	global_store_dwordx4 v[2:3], v[4:7], off sc0 sc1
	s_nop 1
	s_and_saveexec_b64 s[6:7], s[0:1]
	s_cbranch_execz .LBB0_648
	s_mul_i32 s14, s14, 0x43000
	s_ashr_i32 s15, s14, 31
	s_waitcnt lgkmcnt(0)
	v_add_f32_e32 v2, v0, v1
	v_lshl_add_u64 v[0:1], s[14:15], 0, v[112:113]
	s_mul_i32 s44, s33, 0x10c00
	v_lshl_add_u64 v[0:1], v[0:1], 0, s[44:45]
	s_mov_b64 s[14:15], 0x2c0
	v_lshl_add_u64 v[0:1], v[0:1], 0, s[14:15]
	global_store_dword v[0:1], v2, off sc0 sc1
	s_nop 1

.LBB0_1259:
	v_mul_f32_e32 v157, v125, v125
	v_mul_f32_e32 v158, v127, v127
	v_fmac_f32_e32 v157, v124, v124
	v_fmac_f32_e32 v158, v126, v126
	v_add_f32_e32 v157, v157, v158
	v_mul_f32_e32 v158, v121, v121
	v_fmac_f32_e32 v158, v120, v120
	v_cvt_pk_bf16_f32 v124, v124, v125
	v_cvt_pk_bf16_f32 v125, v126, v127
	v_cvt_pk_bf16_f32 v126, v120, v121
	v_mul_f32_e32 v120, v117, v117
	v_mul_f32_e32 v121, v119, v119
	v_fmac_f32_e32 v120, v116, v116
	v_fmac_f32_e32 v121, v118, v118
	v_add_f32_e32 v120, v120, v121
	v_mul_f32_e32 v121, v113, v113
	v_fmac_f32_e32 v121, v112, v112
	v_add_f32_e32 v157, v157, v158
	v_mul_f32_e32 v158, v123, v123
	v_add_f32_e32 v120, v120, v121
	v_mul_f32_e32 v121, v115, v115
	v_fmac_f32_e32 v158, v122, v122
	v_fmac_f32_e32 v121, v114, v114
	v_add_f32_e32 v157, v158, v157
	v_add_f32_e32 v120, v121, v120
	v_lshl_add_u32 v144, s3, 8, v146
	v_add_f32_e32 v120, v157, v120
	v_ashrrev_i32_e32 v145, 31, v144
	v_mov_b32_e32 v121, v120
	s_nop 1
	v_permlane16_swap_b32 v120, v121
	v_lshlrev_b64 v[142:143], 11, v[144:145]
	s_lshl_b32 s6, s10, 8
	v_lshl_add_u64 v[142:143], s[20:21], 0, v[142:143]
	s_ashr_i32 s7, s6, 31
	v_lshl_add_u64 v[142:143], s[6:7], 1, v[142:143]
	s_mov_b32 s71, s57
	v_lshl_add_u64 v[142:143], v[142:143], 0, s[70:71]
	v_lshl_add_u64 v[142:143], v[142:143], 0, v[136:137]
	v_cvt_pk_bf16_f32 v127, v122, v123
	s_mov_b64 s[6:7], 0x100
	global_store_dwordx4 v[142:143], v[124:127], off sc0 sc1
	s_nop 1
	v_cvt_pk_bf16_f32 v116, v116, v117
	v_cvt_pk_bf16_f32 v117, v118, v119
	v_cvt_pk_bf16_f32 v118, v112, v113
	v_cvt_pk_bf16_f32 v119, v114, v115
	s_waitcnt lgkmcnt(0)
	v_add_f32_e32 v114, v120, v121
	v_mov_b32_e32 v115, v114
	s_nop 1
	v_permlane32_swap_b32 v114, v115
	v_lshl_add_u64 v[112:113], v[142:143], 0, s[6:7]
	global_store_dwordx4 v[112:113], v[116:119], off sc0 sc1
	s_nop 1
	v_readlane_b32 s6, v254, 60
	v_lshlrev_b64 v[112:113], 2, v[144:145]
	v_readlane_b32 s7, v254, 61
	s_nop 1
	v_lshl_add_u64 v[112:113], s[6:7], 0, v[112:113]
	s_and_saveexec_b64 s[6:7], s[0:1]
	s_cbranch_execz .LBB0_1261
	s_mul_i32 s8, s10, 0x43000
	s_ashr_i32 s9, s8, 31
	s_waitcnt lgkmcnt(0)
	v_add_f32_e32 v116, v114, v115
	v_lshl_add_u64 v[114:115], s[8:9], 0, v[112:113]
	s_mul_i32 s56, s33, 0x10c00
	v_lshl_add_u64 v[114:115], v[114:115], 0, s[56:57]
	global_store_dword v[114:115], v116, off sc0 sc1
	s_nop 1
.LBB0_1261:
	s_or_b64 exec, exec, s[6:7]
	v_mul_f32_e32 v116, v109, v109
	v_mul_f32_e32 v117, v111, v111
	v_fmac_f32_e32 v116, v108, v108
	v_fmac_f32_e32 v117, v110, v110
	v_add_f32_e32 v116, v116, v117
	v_mul_f32_e32 v117, v105, v105
	v_fmac_f32_e32 v117, v104, v104
	v_cvt_pk_bf16_f32 v108, v108, v109
	v_cvt_pk_bf16_f32 v109, v110, v111
	v_cvt_pk_bf16_f32 v110, v104, v105
	v_mul_f32_e32 v104, v101, v101
	v_mul_f32_e32 v105, v103, v103
	v_fmac_f32_e32 v104, v100, v100
	v_fmac_f32_e32 v105, v102, v102
	v_add_f32_e32 v104, v104, v105
	v_mul_f32_e32 v105, v97, v97
	v_fmac_f32_e32 v105, v96, v96
	v_add_f32_e32 v116, v116, v117
	v_mul_f32_e32 v117, v107, v107
	v_add_f32_e32 v104, v104, v105
	v_mul_f32_e32 v105, v99, v99
	v_fmac_f32_e32 v117, v106, v106
	v_fmac_f32_e32 v105, v98, v98
	v_add_f32_e32 v116, v117, v116
	v_add_f32_e32 v104, v105, v104
	v_add_f32_e32 v104, v116, v104
	v_mov_b32_e32 v105, v104
	s_nop 1
	v_permlane16_swap_b32 v104, v105
	s_mov_b64 s[6:7], 0x8000
	s_waitcnt lgkmcnt(0)
	v_lshl_add_u64 v[114:115], v[142:143], 0, s[6:7]
	v_cvt_pk_bf16_f32 v111, v106, v107
	s_mov_b64 s[6:7], 0x8100
	global_store_dwordx4 v[114:115], v[108:111], off sc0 sc1
	s_nop 1
	v_cvt_pk_bf16_f32 v100, v100, v101
	v_cvt_pk_bf16_f32 v101, v102, v103
	v_cvt_pk_bf16_f32 v102, v96, v97
	v_add_f32_e32 v96, v104, v105
	v_mov_b32_e32 v97, v96
	s_nop 1
	v_permlane32_swap_b32 v96, v97
	v_cvt_pk_bf16_f32 v103, v98, v99
	v_lshl_add_u64 v[98:99], v[142:143], 0, s[6:7]
	global_store_dwordx4 v[98:99], v[100:103], off sc0 sc1
	s_nop 1
	s_and_saveexec_b64 s[6:7], s[0:1]
	s_cbranch_execz .LBB0_1263
	s_waitcnt lgkmcnt(0)
	v_add_f32_e32 v98, v96, v97
	v_or_b32_e32 v96, 16, v144
	v_ashrrev_i32_e32 v97, 31, v96
	v_readlane_b32 s8, v254, 60
	v_lshlrev_b64 v[96:97], 2, v[96:97]
	v_readlane_b32 s9, v254, 61
	s_mul_i32 s56, s33, 0x10c00
	s_nop 0
	v_lshl_add_u64 v[96:97], s[8:9], 0, v[96:97]
	s_mul_i32 s8, s10, 0x43000
	s_ashr_i32 s9, s8, 31
	v_lshl_add_u64 v[96:97], s[8:9], 0, v[96:97]
	v_lshl_add_u64 v[96:97], v[96:97], 0, s[56:57]
	global_store_dword v[96:97], v98, off sc0 sc1
	s_nop 1
.LBB0_1263:
	s_or_b64 exec, exec, s[6:7]
	v_mul_f32_e32 v98, v93, v93
	v_mul_f32_e32 v99, v95, v95
	v_fmac_f32_e32 v98, v92, v92
	v_fmac_f32_e32 v99, v94, v94
	v_add_f32_e32 v98, v98, v99
	v_mul_f32_e32 v99, v89, v89
	v_fmac_f32_e32 v99, v88, v88
	v_cvt_pk_bf16_f32 v92, v92, v93
	v_cvt_pk_bf16_f32 v93, v94, v95
	v_cvt_pk_bf16_f32 v94, v88, v89
	v_mul_f32_e32 v88, v85, v85
	v_mul_f32_e32 v89, v87, v87
	v_fmac_f32_e32 v88, v84, v84
	v_fmac_f32_e32 v89, v86, v86
	v_add_f32_e32 v88, v88, v89
	v_mul_f32_e32 v89, v81, v81
	v_fmac_f32_e32 v89, v80, v80
	v_add_f32_e32 v98, v98, v99
	v_mul_f32_e32 v99, v91, v91
	v_add_f32_e32 v88, v88, v89
	v_mul_f32_e32 v89, v83, v83
	v_fmac_f32_e32 v99, v90, v90
	v_fmac_f32_e32 v89, v82, v82
	v_add_f32_e32 v98, v99, v98
	v_add_f32_e32 v88, v89, v88
	v_add_f32_e32 v88, v98, v88
	v_mov_b32_e32 v89, v88
	s_nop 1
	v_permlane16_swap_b32 v88, v89
	s_mov_b64 s[6:7], 0x10000
	s_waitcnt lgkmcnt(0)
	v_lshl_add_u64 v[96:97], v[142:143], 0, s[6:7]
	v_cvt_pk_bf16_f32 v95, v90, v91
	s_mov_b64 s[6:7], 0x10100
	global_store_dwordx4 v[96:97], v[92:95], off sc0 sc1
	s_nop 1
	v_cvt_pk_bf16_f32 v84, v84, v85
	v_cvt_pk_bf16_f32 v85, v86, v87
	v_cvt_pk_bf16_f32 v86, v80, v81
	v_add_f32_e32 v80, v88, v89
	v_mov_b32_e32 v81, v80
	s_nop 1
	v_permlane32_swap_b32 v80, v81
	v_cvt_pk_bf16_f32 v87, v82, v83
	v_lshl_add_u64 v[82:83], v[142:143], 0, s[6:7]
	global_store_dwordx4 v[82:83], v[84:87], off sc0 sc1
	s_nop 1
	s_and_saveexec_b64 s[6:7], s[0:1]
	s_cbranch_execz .LBB0_1265
	s_waitcnt lgkmcnt(0)
	v_add_f32_e32 v82, v80, v81
	v_or_b32_e32 v80, 32, v144
	v_ashrrev_i32_e32 v81, 31, v80
	v_readlane_b32 s8, v254, 60
	v_lshlrev_b64 v[80:81], 2, v[80:81]
	v_readlane_b32 s9, v254, 61
	s_mul_i32 s56, s33, 0x10c00
	s_nop 0
	v_lshl_add_u64 v[80:81], s[8:9], 0, v[80:81]
	s_mul_i32 s8, s10, 0x43000
	s_ashr_i32 s9, s8, 31
	v_lshl_add_u64 v[80:81], s[8:9], 0, v[80:81]
	v_lshl_add_u64 v[80:81], v[80:81], 0, s[56:57]
	global_store_dword v[80:81], v82, off sc0 sc1
	s_nop 1
.LBB0_1265:
	s_or_b64 exec, exec, s[6:7]
	v_mul_f32_e32 v82, v77, v77
	v_mul_f32_e32 v83, v79, v79
	v_fmac_f32_e32 v82, v76, v76
	v_fmac_f32_e32 v83, v78, v78
	v_add_f32_e32 v82, v82, v83
	v_mul_f32_e32 v83, v73, v73
	v_fmac_f32_e32 v83, v72, v72
	v_cvt_pk_bf16_f32 v76, v76, v77
	v_cvt_pk_bf16_f32 v77, v78, v79
	v_cvt_pk_bf16_f32 v78, v72, v73
	v_mul_f32_e32 v72, v69, v69
	v_mul_f32_e32 v73, v71, v71
	v_fmac_f32_e32 v72, v68, v68
	v_fmac_f32_e32 v73, v70, v70
	v_add_f32_e32 v72, v72, v73
	v_mul_f32_e32 v73, v65, v65
	v_fmac_f32_e32 v73, v64, v64
	v_add_f32_e32 v82, v82, v83
	v_mul_f32_e32 v83, v75, v75
	v_add_f32_e32 v72, v72, v73
	v_mul_f32_e32 v73, v67, v67
	v_fmac_f32_e32 v83, v74, v74
	v_fmac_f32_e32 v73, v66, v66
	v_add_f32_e32 v82, v83, v82
	v_add_f32_e32 v72, v73, v72
	v_add_f32_e32 v72, v82, v72
	v_mov_b32_e32 v73, v72
	s_nop 1
	v_permlane16_swap_b32 v72, v73
	s_mov_b64 s[6:7], 0x18000
	s_waitcnt lgkmcnt(0)
	v_lshl_add_u64 v[80:81], v[142:143], 0, s[6:7]
	v_cvt_pk_bf16_f32 v79, v74, v75
	s_mov_b64 s[6:7], 0x18100
	global_store_dwordx4 v[80:81], v[76:79], off sc0 sc1
	s_nop 1
	v_cvt_pk_bf16_f32 v68, v68, v69
	v_cvt_pk_bf16_f32 v69, v70, v71
	v_cvt_pk_bf16_f32 v70, v64, v65
	v_add_f32_e32 v64, v72, v73
	v_mov_b32_e32 v65, v64
	s_nop 1
	v_permlane32_swap_b32 v64, v65
	v_cvt_pk_bf16_f32 v71, v66, v67
	v_lshl_add_u64 v[66:67], v[142:143], 0, s[6:7]
	global_store_dwordx4 v[66:67], v[68:71], off sc0 sc1
	s_nop 1
	s_and_saveexec_b64 s[6:7], s[0:1]
	s_cbranch_execz .LBB0_1267
	s_waitcnt lgkmcnt(0)
	v_add_f32_e32 v66, v64, v65
	v_or_b32_e32 v64, 48, v144
	v_ashrrev_i32_e32 v65, 31, v64
	v_readlane_b32 s8, v254, 60
	v_lshlrev_b64 v[64:65], 2, v[64:65]
	v_readlane_b32 s9, v254, 61
	s_mul_i32 s56, s33, 0x10c00
	s_nop 0
	v_lshl_add_u64 v[64:65], s[8:9], 0, v[64:65]
	s_mul_i32 s8, s10, 0x43000
	s_ashr_i32 s9, s8, 31
	v_lshl_add_u64 v[64:65], s[8:9], 0, v[64:65]
	v_lshl_add_u64 v[64:65], v[64:65], 0, s[56:57]
	global_store_dword v[64:65], v66, off sc0 sc1
	s_nop 1
.LBB0_1267:
	s_or_b64 exec, exec, s[6:7]
	v_mul_f32_e32 v66, v61, v61
	v_mul_f32_e32 v67, v63, v63
	v_fmac_f32_e32 v66, v60, v60
	v_fmac_f32_e32 v67, v62, v62
	v_add_f32_e32 v66, v66, v67
	v_mul_f32_e32 v67, v57, v57
	v_fmac_f32_e32 v67, v56, v56
	v_cvt_pk_bf16_f32 v60, v60, v61
	v_cvt_pk_bf16_f32 v61, v62, v63
	v_cvt_pk_bf16_f32 v62, v56, v57
	v_mul_f32_e32 v56, v53, v53
	v_mul_f32_e32 v57, v55, v55
	v_fmac_f32_e32 v56, v52, v52
	v_fmac_f32_e32 v57, v54, v54
	v_add_f32_e32 v56, v56, v57
	v_mul_f32_e32 v57, v49, v49
	v_fmac_f32_e32 v57, v48, v48
	v_add_f32_e32 v66, v66, v67
	v_mul_f32_e32 v67, v59, v59
	v_add_f32_e32 v56, v56, v57
	v_mul_f32_e32 v57, v51, v51
	v_fmac_f32_e32 v67, v58, v58
	v_fmac_f32_e32 v57, v50, v50
	v_add_f32_e32 v66, v67, v66
	v_add_f32_e32 v56, v57, v56
	v_add_f32_e32 v56, v66, v56
	v_mov_b32_e32 v57, v56
	s_nop 1
	v_permlane16_swap_b32 v56, v57
	s_mov_b64 s[6:7], 0x40000
	s_waitcnt lgkmcnt(0)
	v_lshl_add_u64 v[64:65], v[142:143], 0, s[6:7]
	v_cvt_pk_bf16_f32 v63, v58, v59
	s_mov_b64 s[6:7], 0x40100
	global_store_dwordx4 v[64:65], v[60:63], off sc0 sc1
	s_nop 1
	v_cvt_pk_bf16_f32 v52, v52, v53
	v_cvt_pk_bf16_f32 v53, v54, v55
	v_cvt_pk_bf16_f32 v54, v48, v49
	v_add_f32_e32 v48, v56, v57
	v_mov_b32_e32 v49, v48
	s_nop 1
	v_permlane32_swap_b32 v48, v49
	v_cvt_pk_bf16_f32 v55, v50, v51
	v_lshl_add_u64 v[50:51], v[142:143], 0, s[6:7]
	global_store_dwordx4 v[50:51], v[52:55], off sc0 sc1
	s_nop 1
	s_and_saveexec_b64 s[6:7], s[0:1]
	s_cbranch_execz .LBB0_1269
	s_mul_i32 s8, s10, 0x43000
	s_ashr_i32 s9, s8, 31
	s_waitcnt lgkmcnt(0)
	v_add_f32_e32 v50, v48, v49
	v_lshl_add_u64 v[48:49], s[8:9], 0, v[112:113]
	s_mul_i32 s56, s33, 0x10c00
	v_lshl_add_u64 v[48:49], v[48:49], 0, s[56:57]
	s_mov_b64 s[8:9], 0x200
	v_lshl_add_u64 v[48:49], v[48:49], 0, s[8:9]
	global_store_dword v[48:49], v50, off sc0 sc1
	s_nop 1
.LBB0_1269:
	s_or_b64 exec, exec, s[6:7]
	v_mul_f32_e32 v50, v45, v45
	v_mul_f32_e32 v51, v47, v47
	v_fmac_f32_e32 v50, v44, v44
	v_fmac_f32_e32 v51, v46, v46
	v_add_f32_e32 v50, v50, v51
	v_mul_f32_e32 v51, v41, v41
	v_fmac_f32_e32 v51, v40, v40
	v_cvt_pk_bf16_f32 v44, v44, v45
	v_cvt_pk_bf16_f32 v45, v46, v47
	v_cvt_pk_bf16_f32 v46, v40, v41
	v_mul_f32_e32 v40, v37, v37
	v_mul_f32_e32 v41, v39, v39
	v_fmac_f32_e32 v40, v36, v36
	v_fmac_f32_e32 v41, v38, v38
	v_add_f32_e32 v40, v40, v41
	v_mul_f32_e32 v41, v33, v33
	v_fmac_f32_e32 v41, v32, v32
	v_add_f32_e32 v50, v50, v51
	v_mul_f32_e32 v51, v43, v43
	v_add_f32_e32 v40, v40, v41
	v_mul_f32_e32 v41, v35, v35
	v_fmac_f32_e32 v51, v42, v42
	v_fmac_f32_e32 v41, v34, v34
	v_add_f32_e32 v50, v51, v50
	v_add_f32_e32 v40, v41, v40
	v_add_f32_e32 v40, v50, v40
	v_mov_b32_e32 v41, v40
	s_nop 1
	v_permlane16_swap_b32 v40, v41
	s_mov_b64 s[6:7], 0x48000
	s_waitcnt lgkmcnt(0)
	v_lshl_add_u64 v[48:49], v[142:143], 0, s[6:7]
	v_cvt_pk_bf16_f32 v47, v42, v43
	s_mov_b64 s[6:7], 0x48100
	global_store_dwordx4 v[48:49], v[44:47], off sc0 sc1
	s_nop 1
	v_cvt_pk_bf16_f32 v36, v36, v37
	v_cvt_pk_bf16_f32 v37, v38, v39
	v_cvt_pk_bf16_f32 v38, v32, v33
	v_add_f32_e32 v32, v40, v41
	v_mov_b32_e32 v33, v32
	s_nop 1
	v_permlane32_swap_b32 v32, v33
	v_cvt_pk_bf16_f32 v39, v34, v35
	v_lshl_add_u64 v[34:35], v[142:143], 0, s[6:7]
	global_store_dwordx4 v[34:35], v[36:39], off sc0 sc1
	s_nop 1
	s_and_saveexec_b64 s[6:7], s[0:1]
	s_cbranch_execz .LBB0_1271
	s_mul_i32 s8, s10, 0x43000
	s_ashr_i32 s9, s8, 31
	s_waitcnt lgkmcnt(0)
	v_add_f32_e32 v34, v32, v33
	v_lshl_add_u64 v[32:33], s[8:9], 0, v[112:113]
	s_mul_i32 s56, s33, 0x10c00
	v_lshl_add_u64 v[32:33], v[32:33], 0, s[56:57]
	s_mov_b64 s[8:9], 0x240
	v_lshl_add_u64 v[32:33], v[32:33], 0, s[8:9]
	global_store_dword v[32:33], v34, off sc0 sc1
	s_nop 1
.LBB0_1271:
	s_or_b64 exec, exec, s[6:7]
	v_mul_f32_e32 v34, v29, v29
	v_mul_f32_e32 v35, v31, v31
	v_fmac_f32_e32 v34, v28, v28
	v_fmac_f32_e32 v35, v30, v30
	v_add_f32_e32 v34, v34, v35
	v_mul_f32_e32 v35, v25, v25
	v_fmac_f32_e32 v35, v24, v24
	v_cvt_pk_bf16_f32 v28, v28, v29
	v_cvt_pk_bf16_f32 v29, v30, v31
	v_cvt_pk_bf16_f32 v30, v24, v25
	v_mul_f32_e32 v24, v21, v21
	v_mul_f32_e32 v25, v23, v23
	v_fmac_f32_e32 v24, v20, v20
	v_fmac_f32_e32 v25, v22, v22
	v_add_f32_e32 v24, v24, v25
	v_mul_f32_e32 v25, v17, v17
	v_fmac_f32_e32 v25, v16, v16
	v_add_f32_e32 v34, v34, v35
	v_mul_f32_e32 v35, v27, v27
	v_add_f32_e32 v24, v24, v25
	v_mul_f32_e32 v25, v19, v19
	v_fmac_f32_e32 v35, v26, v26
	v_fmac_f32_e32 v25, v18, v18
	v_add_f32_e32 v34, v35, v34
	v_add_f32_e32 v24, v25, v24
	v_add_f32_e32 v24, v34, v24
	v_mov_b32_e32 v25, v24
	s_nop 1
	v_permlane16_swap_b32 v24, v25
	s_mov_b64 s[6:7], 0x50000
	s_waitcnt lgkmcnt(0)
	v_lshl_add_u64 v[32:33], v[142:143], 0, s[6:7]
	v_cvt_pk_bf16_f32 v31, v26, v27
	s_mov_b64 s[6:7], 0x50100
	global_store_dwordx4 v[32:33], v[28:31], off sc0 sc1
	s_nop 1
	v_cvt_pk_bf16_f32 v20, v20, v21
	v_cvt_pk_bf16_f32 v21, v22, v23
	v_cvt_pk_bf16_f32 v22, v16, v17
	v_add_f32_e32 v16, v24, v25
	v_mov_b32_e32 v17, v16
	s_nop 1
	v_permlane32_swap_b32 v16, v17
	v_cvt_pk_bf16_f32 v23, v18, v19
	v_lshl_add_u64 v[18:19], v[142:143], 0, s[6:7]
	global_store_dwordx4 v[18:19], v[20:23], off sc0 sc1
	s_nop 1
	s_and_saveexec_b64 s[6:7], s[0:1]
	s_cbranch_execz .LBB0_1273
	s_mul_i32 s8, s10, 0x43000
	s_ashr_i32 s9, s8, 31
	s_waitcnt lgkmcnt(0)
	v_add_f32_e32 v18, v16, v17
	v_lshl_add_u64 v[16:17], s[8:9], 0, v[112:113]
	s_mul_i32 s56, s33, 0x10c00
	v_lshl_add_u64 v[16:17], v[16:17], 0, s[56:57]
	s_mov_b64 s[8:9], 0x280
	v_lshl_add_u64 v[16:17], v[16:17], 0, s[8:9]
	global_store_dword v[16:17], v18, off sc0 sc1
	s_nop 1
.LBB0_1273:
	s_or_b64 exec, exec, s[6:7]
	v_mul_f32_e32 v18, v13, v13
	v_mul_f32_e32 v19, v15, v15
	v_fmac_f32_e32 v18, v12, v12
	v_fmac_f32_e32 v19, v14, v14
	v_add_f32_e32 v18, v18, v19
	v_mul_f32_e32 v19, v9, v9
	v_fmac_f32_e32 v19, v8, v8
	v_cvt_pk_bf16_f32 v12, v12, v13
	v_cvt_pk_bf16_f32 v13, v14, v15
	v_cvt_pk_bf16_f32 v14, v8, v9
	v_mul_f32_e32 v8, v5, v5
	v_mul_f32_e32 v9, v7, v7
	v_fmac_f32_e32 v8, v4, v4
	v_fmac_f32_e32 v9, v6, v6
	v_add_f32_e32 v8, v8, v9
	v_mul_f32_e32 v9, v1, v1
	v_fmac_f32_e32 v9, v0, v0
	v_add_f32_e32 v18, v18, v19
	v_mul_f32_e32 v19, v11, v11
	v_add_f32_e32 v8, v8, v9
	v_mul_f32_e32 v9, v3, v3
	v_fmac_f32_e32 v19, v10, v10
	v_fmac_f32_e32 v9, v2, v2
	v_add_f32_e32 v18, v19, v18
	v_add_f32_e32 v8, v9, v8
	v_add_f32_e32 v8, v18, v8
	v_mov_b32_e32 v9, v8
	s_nop 1
	v_permlane16_swap_b32 v8, v9
	s_mov_b64 s[6:7], 0x58000
	s_waitcnt lgkmcnt(0)
	v_lshl_add_u64 v[16:17], v[142:143], 0, s[6:7]
	v_cvt_pk_bf16_f32 v15, v10, v11
	s_mov_b64 s[6:7], 0x58100
	global_store_dwordx4 v[16:17], v[12:15], off sc0 sc1
	s_nop 1
	v_cvt_pk_bf16_f32 v4, v4, v5
	v_cvt_pk_bf16_f32 v5, v6, v7
	v_cvt_pk_bf16_f32 v6, v0, v1
	v_add_f32_e32 v0, v8, v9
	v_mov_b32_e32 v1, v0
	s_nop 1
	v_permlane32_swap_b32 v0, v1
	v_cvt_pk_bf16_f32 v7, v2, v3
	v_lshl_add_u64 v[2:3], v[142:143], 0, s[6:7]
	global_store_dwordx4 v[2:3], v[4:7], off sc0 sc1
	s_nop 1
	s_and_saveexec_b64 s[6:7], s[0:1]
	s_cbranch_execz .LBB0_1275
	s_mul_i32 s8, s10, 0x43000
	s_ashr_i32 s9, s8, 31
	s_waitcnt lgkmcnt(0)
	v_add_f32_e32 v2, v0, v1
	v_lshl_add_u64 v[0:1], s[8:9], 0, v[112:113]
	s_mul_i32 s56, s33, 0x10c00
	v_lshl_add_u64 v[0:1], v[0:1], 0, s[56:57]
	s_mov_b64 s[8:9], 0x2c0
	v_lshl_add_u64 v[0:1], v[0:1], 0, s[8:9]
	global_store_dword v[0:1], v2, off sc0 sc1
	s_nop 1

.LBB0_1876:
	v_mul_f32_e32 v157, v125, v125
	v_mul_f32_e32 v158, v127, v127
	v_fmac_f32_e32 v157, v124, v124
	v_fmac_f32_e32 v158, v126, v126
	v_add_f32_e32 v157, v157, v158
	v_mul_f32_e32 v158, v121, v121
	v_fmac_f32_e32 v158, v120, v120
	v_cvt_pk_bf16_f32 v124, v124, v125
	v_cvt_pk_bf16_f32 v125, v126, v127
	v_cvt_pk_bf16_f32 v126, v120, v121
	v_mul_f32_e32 v120, v117, v117
	v_mul_f32_e32 v121, v119, v119
	v_fmac_f32_e32 v120, v116, v116
	v_fmac_f32_e32 v121, v118, v118
	v_add_f32_e32 v120, v120, v121
	v_mul_f32_e32 v121, v113, v113
	v_fmac_f32_e32 v121, v112, v112
	v_add_f32_e32 v157, v157, v158
	v_mul_f32_e32 v158, v123, v123
	v_add_f32_e32 v120, v120, v121
	v_mul_f32_e32 v121, v115, v115
	v_fmac_f32_e32 v158, v122, v122
	v_fmac_f32_e32 v121, v114, v114
	v_add_f32_e32 v157, v158, v157
	v_add_f32_e32 v120, v121, v120
	v_lshl_add_u32 v144, s52, 8, v146
	v_add_f32_e32 v120, v157, v120
	v_ashrrev_i32_e32 v145, 31, v144
	v_mov_b32_e32 v121, v120
	s_nop 1
	v_permlane16_swap_b32 v120, v121
	v_lshlrev_b64 v[142:143], 11, v[144:145]
	s_lshl_b32 s6, s54, 8
	v_lshl_add_u64 v[142:143], s[20:21], 0, v[142:143]
	s_ashr_i32 s7, s6, 31
	v_lshl_add_u64 v[142:143], s[6:7], 1, v[142:143]
	s_mov_b32 s65, s57
	v_lshl_add_u64 v[142:143], v[142:143], 0, s[64:65]
	v_lshl_add_u64 v[142:143], v[142:143], 0, v[136:137]
	v_cvt_pk_bf16_f32 v127, v122, v123
	s_mov_b64 s[6:7], 0x100
	global_store_dwordx4 v[142:143], v[124:127], off sc0 sc1
	s_nop 1
	v_cvt_pk_bf16_f32 v116, v116, v117
	v_cvt_pk_bf16_f32 v117, v118, v119
	v_cvt_pk_bf16_f32 v118, v112, v113
	v_cvt_pk_bf16_f32 v119, v114, v115
	s_waitcnt lgkmcnt(0)
	v_add_f32_e32 v114, v120, v121
	v_mov_b32_e32 v115, v114
	s_nop 1
	v_permlane32_swap_b32 v114, v115
	v_lshl_add_u64 v[112:113], v[142:143], 0, s[6:7]
	global_store_dwordx4 v[112:113], v[116:119], off sc0 sc1
	s_nop 1
	v_readlane_b32 s6, v254, 60
	v_lshlrev_b64 v[112:113], 2, v[144:145]
	v_readlane_b32 s7, v254, 61
	s_nop 1
	v_lshl_add_u64 v[112:113], s[6:7], 0, v[112:113]
	s_and_saveexec_b64 s[6:7], s[0:1]
	s_cbranch_execz .LBB0_1878
	s_mul_i32 s8, s54, 0x43000
	s_ashr_i32 s9, s8, 31
	s_waitcnt lgkmcnt(0)
	v_add_f32_e32 v116, v114, v115
	v_lshl_add_u64 v[114:115], s[8:9], 0, v[112:113]
	s_mul_i32 s56, s17, 0x10c00
	v_lshl_add_u64 v[114:115], v[114:115], 0, s[56:57]
	global_store_dword v[114:115], v116, off sc0 sc1
	s_nop 1
.LBB0_1878:
	s_or_b64 exec, exec, s[6:7]
	v_mul_f32_e32 v116, v109, v109
	v_mul_f32_e32 v117, v111, v111
	v_fmac_f32_e32 v116, v108, v108
	v_fmac_f32_e32 v117, v110, v110
	v_add_f32_e32 v116, v116, v117
	v_mul_f32_e32 v117, v105, v105
	v_fmac_f32_e32 v117, v104, v104
	v_cvt_pk_bf16_f32 v108, v108, v109
	v_cvt_pk_bf16_f32 v109, v110, v111
	v_cvt_pk_bf16_f32 v110, v104, v105
	v_mul_f32_e32 v104, v101, v101
	v_mul_f32_e32 v105, v103, v103
	v_fmac_f32_e32 v104, v100, v100
	v_fmac_f32_e32 v105, v102, v102
	v_add_f32_e32 v104, v104, v105
	v_mul_f32_e32 v105, v97, v97
	v_fmac_f32_e32 v105, v96, v96
	v_add_f32_e32 v116, v116, v117
	v_mul_f32_e32 v117, v107, v107
	v_add_f32_e32 v104, v104, v105
	v_mul_f32_e32 v105, v99, v99
	v_fmac_f32_e32 v117, v106, v106
	v_fmac_f32_e32 v105, v98, v98
	v_add_f32_e32 v116, v117, v116
	v_add_f32_e32 v104, v105, v104
	v_add_f32_e32 v104, v116, v104
	v_mov_b32_e32 v105, v104
	s_nop 1
	v_permlane16_swap_b32 v104, v105
	s_mov_b64 s[6:7], 0x8000
	s_waitcnt lgkmcnt(0)
	v_lshl_add_u64 v[114:115], v[142:143], 0, s[6:7]
	v_cvt_pk_bf16_f32 v111, v106, v107
	s_mov_b64 s[6:7], 0x8100
	global_store_dwordx4 v[114:115], v[108:111], off sc0 sc1
	s_nop 1
	v_cvt_pk_bf16_f32 v100, v100, v101
	v_cvt_pk_bf16_f32 v101, v102, v103
	v_cvt_pk_bf16_f32 v102, v96, v97
	v_add_f32_e32 v96, v104, v105
	v_mov_b32_e32 v97, v96
	s_nop 1
	v_permlane32_swap_b32 v96, v97
	v_cvt_pk_bf16_f32 v103, v98, v99
	v_lshl_add_u64 v[98:99], v[142:143], 0, s[6:7]
	global_store_dwordx4 v[98:99], v[100:103], off sc0 sc1
	s_nop 1
	s_and_saveexec_b64 s[6:7], s[0:1]
	s_cbranch_execz .LBB0_1880
	s_waitcnt lgkmcnt(0)
	v_add_f32_e32 v98, v96, v97
	v_or_b32_e32 v96, 16, v144
	v_ashrrev_i32_e32 v97, 31, v96
	v_readlane_b32 s8, v254, 60
	v_lshlrev_b64 v[96:97], 2, v[96:97]
	v_readlane_b32 s9, v254, 61
	s_mul_i32 s56, s17, 0x10c00
	s_nop 0
	v_lshl_add_u64 v[96:97], s[8:9], 0, v[96:97]
	s_mul_i32 s8, s54, 0x43000
	s_ashr_i32 s9, s8, 31
	v_lshl_add_u64 v[96:97], s[8:9], 0, v[96:97]
	v_lshl_add_u64 v[96:97], v[96:97], 0, s[56:57]
	global_store_dword v[96:97], v98, off sc0 sc1
	s_nop 1
.LBB0_1880:
	s_or_b64 exec, exec, s[6:7]
	v_mul_f32_e32 v98, v93, v93
	v_mul_f32_e32 v99, v95, v95
	v_fmac_f32_e32 v98, v92, v92
	v_fmac_f32_e32 v99, v94, v94
	v_add_f32_e32 v98, v98, v99
	v_mul_f32_e32 v99, v89, v89
	v_fmac_f32_e32 v99, v88, v88
	v_cvt_pk_bf16_f32 v92, v92, v93
	v_cvt_pk_bf16_f32 v93, v94, v95
	v_cvt_pk_bf16_f32 v94, v88, v89
	v_mul_f32_e32 v88, v85, v85
	v_mul_f32_e32 v89, v87, v87
	v_fmac_f32_e32 v88, v84, v84
	v_fmac_f32_e32 v89, v86, v86
	v_add_f32_e32 v88, v88, v89
	v_mul_f32_e32 v89, v81, v81
	v_fmac_f32_e32 v89, v80, v80
	v_add_f32_e32 v98, v98, v99
	v_mul_f32_e32 v99, v91, v91
	v_add_f32_e32 v88, v88, v89
	v_mul_f32_e32 v89, v83, v83
	v_fmac_f32_e32 v99, v90, v90
	v_fmac_f32_e32 v89, v82, v82
	v_add_f32_e32 v98, v99, v98
	v_add_f32_e32 v88, v89, v88
	v_add_f32_e32 v88, v98, v88
	v_mov_b32_e32 v89, v88
	s_nop 1
	v_permlane16_swap_b32 v88, v89
	s_mov_b64 s[6:7], 0x10000
	s_waitcnt lgkmcnt(0)
	v_lshl_add_u64 v[96:97], v[142:143], 0, s[6:7]
	v_cvt_pk_bf16_f32 v95, v90, v91
	s_mov_b64 s[6:7], 0x10100
	global_store_dwordx4 v[96:97], v[92:95], off sc0 sc1
	s_nop 1
	v_cvt_pk_bf16_f32 v84, v84, v85
	v_cvt_pk_bf16_f32 v85, v86, v87
	v_cvt_pk_bf16_f32 v86, v80, v81
	v_add_f32_e32 v80, v88, v89
	v_mov_b32_e32 v81, v80
	s_nop 1
	v_permlane32_swap_b32 v80, v81
	v_cvt_pk_bf16_f32 v87, v82, v83
	v_lshl_add_u64 v[82:83], v[142:143], 0, s[6:7]
	global_store_dwordx4 v[82:83], v[84:87], off sc0 sc1
	s_nop 1
	s_and_saveexec_b64 s[6:7], s[0:1]
	s_cbranch_execz .LBB0_1882
	s_waitcnt lgkmcnt(0)
	v_add_f32_e32 v82, v80, v81
	v_or_b32_e32 v80, 32, v144
	v_ashrrev_i32_e32 v81, 31, v80
	v_readlane_b32 s8, v254, 60
	v_lshlrev_b64 v[80:81], 2, v[80:81]
	v_readlane_b32 s9, v254, 61
	s_mul_i32 s56, s17, 0x10c00
	s_nop 0
	v_lshl_add_u64 v[80:81], s[8:9], 0, v[80:81]
	s_mul_i32 s8, s54, 0x43000
	s_ashr_i32 s9, s8, 31
	v_lshl_add_u64 v[80:81], s[8:9], 0, v[80:81]
	v_lshl_add_u64 v[80:81], v[80:81], 0, s[56:57]
	global_store_dword v[80:81], v82, off sc0 sc1
	s_nop 1
.LBB0_1882:
	s_or_b64 exec, exec, s[6:7]
	v_mul_f32_e32 v82, v77, v77
	v_mul_f32_e32 v83, v79, v79
	v_fmac_f32_e32 v82, v76, v76
	v_fmac_f32_e32 v83, v78, v78
	v_add_f32_e32 v82, v82, v83
	v_mul_f32_e32 v83, v73, v73
	v_fmac_f32_e32 v83, v72, v72
	v_cvt_pk_bf16_f32 v76, v76, v77
	v_cvt_pk_bf16_f32 v77, v78, v79
	v_cvt_pk_bf16_f32 v78, v72, v73
	v_mul_f32_e32 v72, v69, v69
	v_mul_f32_e32 v73, v71, v71
	v_fmac_f32_e32 v72, v68, v68
	v_fmac_f32_e32 v73, v70, v70
	v_add_f32_e32 v72, v72, v73
	v_mul_f32_e32 v73, v65, v65
	v_fmac_f32_e32 v73, v64, v64
	v_add_f32_e32 v82, v82, v83
	v_mul_f32_e32 v83, v75, v75
	v_add_f32_e32 v72, v72, v73
	v_mul_f32_e32 v73, v67, v67
	v_fmac_f32_e32 v83, v74, v74
	v_fmac_f32_e32 v73, v66, v66
	v_add_f32_e32 v82, v83, v82
	v_add_f32_e32 v72, v73, v72
	v_add_f32_e32 v72, v82, v72
	v_mov_b32_e32 v73, v72
	s_nop 1
	v_permlane16_swap_b32 v72, v73
	s_mov_b64 s[6:7], 0x18000
	s_waitcnt lgkmcnt(0)
	v_lshl_add_u64 v[80:81], v[142:143], 0, s[6:7]
	v_cvt_pk_bf16_f32 v79, v74, v75
	s_mov_b64 s[6:7], 0x18100
	global_store_dwordx4 v[80:81], v[76:79], off sc0 sc1
	s_nop 1
	v_cvt_pk_bf16_f32 v68, v68, v69
	v_cvt_pk_bf16_f32 v69, v70, v71
	v_cvt_pk_bf16_f32 v70, v64, v65
	v_add_f32_e32 v64, v72, v73
	v_mov_b32_e32 v65, v64
	s_nop 1
	v_permlane32_swap_b32 v64, v65
	v_cvt_pk_bf16_f32 v71, v66, v67
	v_lshl_add_u64 v[66:67], v[142:143], 0, s[6:7]
	global_store_dwordx4 v[66:67], v[68:71], off sc0 sc1
	s_nop 1
	s_and_saveexec_b64 s[6:7], s[0:1]
	s_cbranch_execz .LBB0_1884
	s_waitcnt lgkmcnt(0)
	v_add_f32_e32 v66, v64, v65
	v_or_b32_e32 v64, 48, v144
	v_ashrrev_i32_e32 v65, 31, v64
	v_readlane_b32 s8, v254, 60
	v_lshlrev_b64 v[64:65], 2, v[64:65]
	v_readlane_b32 s9, v254, 61
	s_mul_i32 s56, s17, 0x10c00
	s_nop 0
	v_lshl_add_u64 v[64:65], s[8:9], 0, v[64:65]
	s_mul_i32 s8, s54, 0x43000
	s_ashr_i32 s9, s8, 31
	v_lshl_add_u64 v[64:65], s[8:9], 0, v[64:65]
	v_lshl_add_u64 v[64:65], v[64:65], 0, s[56:57]
	global_store_dword v[64:65], v66, off sc0 sc1
	s_nop 1
.LBB0_1884:
	s_or_b64 exec, exec, s[6:7]
	v_mul_f32_e32 v66, v61, v61
	v_mul_f32_e32 v67, v63, v63
	v_fmac_f32_e32 v66, v60, v60
	v_fmac_f32_e32 v67, v62, v62
	v_add_f32_e32 v66, v66, v67
	v_mul_f32_e32 v67, v57, v57
	v_fmac_f32_e32 v67, v56, v56
	v_cvt_pk_bf16_f32 v60, v60, v61
	v_cvt_pk_bf16_f32 v61, v62, v63
	v_cvt_pk_bf16_f32 v62, v56, v57
	v_mul_f32_e32 v56, v53, v53
	v_mul_f32_e32 v57, v55, v55
	v_fmac_f32_e32 v56, v52, v52
	v_fmac_f32_e32 v57, v54, v54
	v_add_f32_e32 v56, v56, v57
	v_mul_f32_e32 v57, v49, v49
	v_fmac_f32_e32 v57, v48, v48
	v_add_f32_e32 v66, v66, v67
	v_mul_f32_e32 v67, v59, v59
	v_add_f32_e32 v56, v56, v57
	v_mul_f32_e32 v57, v51, v51
	v_fmac_f32_e32 v67, v58, v58
	v_fmac_f32_e32 v57, v50, v50
	v_add_f32_e32 v66, v67, v66
	v_add_f32_e32 v56, v57, v56
	v_add_f32_e32 v56, v66, v56
	v_mov_b32_e32 v57, v56
	s_nop 1
	v_permlane16_swap_b32 v56, v57
	s_mov_b64 s[6:7], 0x40000
	s_waitcnt lgkmcnt(0)
	v_lshl_add_u64 v[64:65], v[142:143], 0, s[6:7]
	v_cvt_pk_bf16_f32 v63, v58, v59
	s_mov_b64 s[6:7], 0x40100
	global_store_dwordx4 v[64:65], v[60:63], off sc0 sc1
	s_nop 1
	v_cvt_pk_bf16_f32 v52, v52, v53
	v_cvt_pk_bf16_f32 v53, v54, v55
	v_cvt_pk_bf16_f32 v54, v48, v49
	v_add_f32_e32 v48, v56, v57
	v_mov_b32_e32 v49, v48
	s_nop 1
	v_permlane32_swap_b32 v48, v49
	v_cvt_pk_bf16_f32 v55, v50, v51
	v_lshl_add_u64 v[50:51], v[142:143], 0, s[6:7]
	global_store_dwordx4 v[50:51], v[52:55], off sc0 sc1
	s_nop 1
	s_and_saveexec_b64 s[6:7], s[0:1]
	s_cbranch_execz .LBB0_1886
	s_mul_i32 s8, s54, 0x43000
	s_ashr_i32 s9, s8, 31
	s_waitcnt lgkmcnt(0)
	v_add_f32_e32 v50, v48, v49
	v_lshl_add_u64 v[48:49], s[8:9], 0, v[112:113]
	s_mul_i32 s56, s17, 0x10c00
	v_lshl_add_u64 v[48:49], v[48:49], 0, s[56:57]
	s_mov_b64 s[8:9], 0x200
	v_lshl_add_u64 v[48:49], v[48:49], 0, s[8:9]
	global_store_dword v[48:49], v50, off sc0 sc1
	s_nop 1
.LBB0_1886:
	s_or_b64 exec, exec, s[6:7]
	v_mul_f32_e32 v50, v45, v45
	v_mul_f32_e32 v51, v47, v47
	v_fmac_f32_e32 v50, v44, v44
	v_fmac_f32_e32 v51, v46, v46
	v_add_f32_e32 v50, v50, v51
	v_mul_f32_e32 v51, v41, v41
	v_fmac_f32_e32 v51, v40, v40
	v_cvt_pk_bf16_f32 v44, v44, v45
	v_cvt_pk_bf16_f32 v45, v46, v47
	v_cvt_pk_bf16_f32 v46, v40, v41
	v_mul_f32_e32 v40, v37, v37
	v_mul_f32_e32 v41, v39, v39
	v_fmac_f32_e32 v40, v36, v36
	v_fmac_f32_e32 v41, v38, v38
	v_add_f32_e32 v40, v40, v41
	v_mul_f32_e32 v41, v33, v33
	v_fmac_f32_e32 v41, v32, v32
	v_add_f32_e32 v50, v50, v51
	v_mul_f32_e32 v51, v43, v43
	v_add_f32_e32 v40, v40, v41
	v_mul_f32_e32 v41, v35, v35
	v_fmac_f32_e32 v51, v42, v42
	v_fmac_f32_e32 v41, v34, v34
	v_add_f32_e32 v50, v51, v50
	v_add_f32_e32 v40, v41, v40
	v_add_f32_e32 v40, v50, v40
	v_mov_b32_e32 v41, v40
	s_nop 1
	v_permlane16_swap_b32 v40, v41
	s_mov_b64 s[6:7], 0x48000
	s_waitcnt lgkmcnt(0)
	v_lshl_add_u64 v[48:49], v[142:143], 0, s[6:7]
	v_cvt_pk_bf16_f32 v47, v42, v43
	s_mov_b64 s[6:7], 0x48100
	global_store_dwordx4 v[48:49], v[44:47], off sc0 sc1
	s_nop 1
	v_cvt_pk_bf16_f32 v36, v36, v37
	v_cvt_pk_bf16_f32 v37, v38, v39
	v_cvt_pk_bf16_f32 v38, v32, v33
	v_add_f32_e32 v32, v40, v41
	v_mov_b32_e32 v33, v32
	s_nop 1
	v_permlane32_swap_b32 v32, v33
	v_cvt_pk_bf16_f32 v39, v34, v35
	v_lshl_add_u64 v[34:35], v[142:143], 0, s[6:7]
	global_store_dwordx4 v[34:35], v[36:39], off sc0 sc1
	s_nop 1
	s_and_saveexec_b64 s[6:7], s[0:1]
	s_cbranch_execz .LBB0_1888
	s_mul_i32 s8, s54, 0x43000
	s_ashr_i32 s9, s8, 31
	s_waitcnt lgkmcnt(0)
	v_add_f32_e32 v34, v32, v33
	v_lshl_add_u64 v[32:33], s[8:9], 0, v[112:113]
	s_mul_i32 s56, s17, 0x10c00
	v_lshl_add_u64 v[32:33], v[32:33], 0, s[56:57]
	s_mov_b64 s[8:9], 0x240
	v_lshl_add_u64 v[32:33], v[32:33], 0, s[8:9]
	global_store_dword v[32:33], v34, off sc0 sc1
	s_nop 1
.LBB0_1888:
	s_or_b64 exec, exec, s[6:7]
	v_mul_f32_e32 v34, v29, v29
	v_mul_f32_e32 v35, v31, v31
	v_fmac_f32_e32 v34, v28, v28
	v_fmac_f32_e32 v35, v30, v30
	v_add_f32_e32 v34, v34, v35
	v_mul_f32_e32 v35, v25, v25
	v_fmac_f32_e32 v35, v24, v24
	v_cvt_pk_bf16_f32 v28, v28, v29
	v_cvt_pk_bf16_f32 v29, v30, v31
	v_cvt_pk_bf16_f32 v30, v24, v25
	v_mul_f32_e32 v24, v21, v21
	v_mul_f32_e32 v25, v23, v23
	v_fmac_f32_e32 v24, v20, v20
	v_fmac_f32_e32 v25, v22, v22
	v_add_f32_e32 v24, v24, v25
	v_mul_f32_e32 v25, v17, v17
	v_fmac_f32_e32 v25, v16, v16
	v_add_f32_e32 v34, v34, v35
	v_mul_f32_e32 v35, v27, v27
	v_add_f32_e32 v24, v24, v25
	v_mul_f32_e32 v25, v19, v19
	v_fmac_f32_e32 v35, v26, v26
	v_fmac_f32_e32 v25, v18, v18
	v_add_f32_e32 v34, v35, v34
	v_add_f32_e32 v24, v25, v24
	v_add_f32_e32 v24, v34, v24
	v_mov_b32_e32 v25, v24
	s_nop 1
	v_permlane16_swap_b32 v24, v25
	s_mov_b64 s[6:7], 0x50000
	s_waitcnt lgkmcnt(0)
	v_lshl_add_u64 v[32:33], v[142:143], 0, s[6:7]
	v_cvt_pk_bf16_f32 v31, v26, v27
	s_mov_b64 s[6:7], 0x50100
	global_store_dwordx4 v[32:33], v[28:31], off sc0 sc1
	s_nop 1
	v_cvt_pk_bf16_f32 v20, v20, v21
	v_cvt_pk_bf16_f32 v21, v22, v23
	v_cvt_pk_bf16_f32 v22, v16, v17
	v_add_f32_e32 v16, v24, v25
	v_mov_b32_e32 v17, v16
	s_nop 1
	v_permlane32_swap_b32 v16, v17
	v_cvt_pk_bf16_f32 v23, v18, v19
	v_lshl_add_u64 v[18:19], v[142:143], 0, s[6:7]
	global_store_dwordx4 v[18:19], v[20:23], off sc0 sc1
	s_nop 1
	s_and_saveexec_b64 s[6:7], s[0:1]
	s_cbranch_execz .LBB0_1890
	s_mul_i32 s8, s54, 0x43000
	s_ashr_i32 s9, s8, 31
	s_waitcnt lgkmcnt(0)
	v_add_f32_e32 v18, v16, v17
	v_lshl_add_u64 v[16:17], s[8:9], 0, v[112:113]
	s_mul_i32 s56, s17, 0x10c00
	v_lshl_add_u64 v[16:17], v[16:17], 0, s[56:57]
	s_mov_b64 s[8:9], 0x280
	v_lshl_add_u64 v[16:17], v[16:17], 0, s[8:9]
	global_store_dword v[16:17], v18, off sc0 sc1
	s_nop 1
.LBB0_1890:
	s_or_b64 exec, exec, s[6:7]
	v_mul_f32_e32 v18, v13, v13
	v_mul_f32_e32 v19, v15, v15
	v_fmac_f32_e32 v18, v12, v12
	v_fmac_f32_e32 v19, v14, v14
	v_add_f32_e32 v18, v18, v19
	v_mul_f32_e32 v19, v9, v9
	v_fmac_f32_e32 v19, v8, v8
	v_cvt_pk_bf16_f32 v12, v12, v13
	v_cvt_pk_bf16_f32 v13, v14, v15
	v_cvt_pk_bf16_f32 v14, v8, v9
	v_mul_f32_e32 v8, v5, v5
	v_mul_f32_e32 v9, v7, v7
	v_fmac_f32_e32 v8, v4, v4
	v_fmac_f32_e32 v9, v6, v6
	v_add_f32_e32 v8, v8, v9
	v_mul_f32_e32 v9, v1, v1
	v_fmac_f32_e32 v9, v0, v0
	v_add_f32_e32 v18, v18, v19
	v_mul_f32_e32 v19, v11, v11
	v_add_f32_e32 v8, v8, v9
	v_mul_f32_e32 v9, v3, v3
	v_fmac_f32_e32 v19, v10, v10
	v_fmac_f32_e32 v9, v2, v2
	v_add_f32_e32 v18, v19, v18
	v_add_f32_e32 v8, v9, v8
	v_add_f32_e32 v8, v18, v8
	v_mov_b32_e32 v9, v8
	s_nop 1
	v_permlane16_swap_b32 v8, v9
	s_mov_b64 s[6:7], 0x58000
	s_waitcnt lgkmcnt(0)
	v_lshl_add_u64 v[16:17], v[142:143], 0, s[6:7]
	v_cvt_pk_bf16_f32 v15, v10, v11
	s_mov_b64 s[6:7], 0x58100
	global_store_dwordx4 v[16:17], v[12:15], off sc0 sc1
	s_nop 1
	v_cvt_pk_bf16_f32 v4, v4, v5
	v_cvt_pk_bf16_f32 v5, v6, v7
	v_cvt_pk_bf16_f32 v6, v0, v1
	v_add_f32_e32 v0, v8, v9
	v_mov_b32_e32 v1, v0
	s_nop 1
	v_permlane32_swap_b32 v0, v1
	v_cvt_pk_bf16_f32 v7, v2, v3
	v_lshl_add_u64 v[2:3], v[142:143], 0, s[6:7]
	global_store_dwordx4 v[2:3], v[4:7], off sc0 sc1
	s_nop 1
	s_and_saveexec_b64 s[6:7], s[0:1]
	s_cbranch_execz .LBB0_1892
	s_mul_i32 s8, s54, 0x43000
	s_ashr_i32 s9, s8, 31
	s_waitcnt lgkmcnt(0)
	v_add_f32_e32 v2, v0, v1
	v_lshl_add_u64 v[0:1], s[8:9], 0, v[112:113]
	s_mul_i32 s56, s17, 0x10c00
	v_lshl_add_u64 v[0:1], v[0:1], 0, s[56:57]
	s_mov_b64 s[8:9], 0x2c0
	v_lshl_add_u64 v[0:1], v[0:1], 0, s[8:9]
	global_store_dword v[0:1], v2, off sc0 sc1
	s_nop 1

.LBB0_2304:
	v_mul_f32_e32 v157, v125, v125
	v_mul_f32_e32 v158, v127, v127
	v_fmac_f32_e32 v157, v124, v124
	v_fmac_f32_e32 v158, v126, v126
	v_add_f32_e32 v157, v157, v158
	v_mul_f32_e32 v158, v121, v121
	v_fmac_f32_e32 v158, v120, v120
	v_cvt_pk_bf16_f32 v124, v124, v125
	v_cvt_pk_bf16_f32 v125, v126, v127
	v_cvt_pk_bf16_f32 v126, v120, v121
	v_mul_f32_e32 v120, v117, v117
	v_mul_f32_e32 v121, v119, v119
	v_fmac_f32_e32 v120, v116, v116
	v_fmac_f32_e32 v121, v118, v118
	v_add_f32_e32 v120, v120, v121
	v_mul_f32_e32 v121, v113, v113
	v_fmac_f32_e32 v121, v112, v112
	v_add_f32_e32 v157, v157, v158
	v_mul_f32_e32 v158, v123, v123
	v_add_f32_e32 v120, v120, v121
	v_mul_f32_e32 v121, v115, v115
	v_fmac_f32_e32 v158, v122, v122
	v_fmac_f32_e32 v121, v114, v114
	v_add_f32_e32 v157, v158, v157
	v_add_f32_e32 v120, v121, v120
	v_lshl_add_u32 v144, s12, 8, v146
	v_add_f32_e32 v120, v157, v120
	v_ashrrev_i32_e32 v145, 31, v144
	v_mov_b32_e32 v121, v120
	s_nop 1
	v_permlane16_swap_b32 v120, v121
	v_lshlrev_b64 v[142:143], 11, v[144:145]
	s_lshl_b32 s8, s13, 8
	v_lshl_add_u64 v[142:143], s[20:21], 0, v[142:143]
	s_ashr_i32 s9, s8, 31
	v_lshl_add_u64 v[142:143], s[8:9], 1, v[142:143]
	s_mov_b32 s41, s15
	v_lshl_add_u64 v[142:143], v[142:143], 0, s[40:41]
	v_lshl_add_u64 v[142:143], v[142:143], 0, v[136:137]
	v_cvt_pk_bf16_f32 v127, v122, v123
	s_mov_b64 s[8:9], 0x100
	global_store_dwordx4 v[142:143], v[124:127], off sc0 sc1
	s_nop 1
	v_cvt_pk_bf16_f32 v116, v116, v117
	v_cvt_pk_bf16_f32 v117, v118, v119
	v_cvt_pk_bf16_f32 v118, v112, v113
	v_cvt_pk_bf16_f32 v119, v114, v115
	s_waitcnt lgkmcnt(0)
	v_add_f32_e32 v114, v120, v121
	v_mov_b32_e32 v115, v114
	s_nop 1
	v_permlane32_swap_b32 v114, v115
	v_lshl_add_u64 v[112:113], v[142:143], 0, s[8:9]
	global_store_dwordx4 v[112:113], v[116:119], off sc0 sc1
	s_nop 1
	v_readlane_b32 s8, v254, 60
	v_lshlrev_b64 v[112:113], 2, v[144:145]
	v_readlane_b32 s9, v254, 61
	s_nop 1
	v_lshl_add_u64 v[112:113], s[8:9], 0, v[112:113]
	s_and_saveexec_b64 s[8:9], s[0:1]
	s_cbranch_execz .LBB0_2306
	s_mul_i32 s18, s13, 0x43000
	s_ashr_i32 s19, s18, 31
	s_waitcnt lgkmcnt(0)
	v_add_f32_e32 v116, v114, v115
	v_lshl_add_u64 v[114:115], s[18:19], 0, v[112:113]
	s_mul_i32 s14, s48, 0x10c00
	v_lshl_add_u64 v[114:115], v[114:115], 0, s[14:15]
	global_store_dword v[114:115], v116, off sc0 sc1
	s_nop 1
.LBB0_2306:
	s_or_b64 exec, exec, s[8:9]
	v_mul_f32_e32 v116, v109, v109
	v_mul_f32_e32 v117, v111, v111
	v_fmac_f32_e32 v116, v108, v108
	v_fmac_f32_e32 v117, v110, v110
	v_add_f32_e32 v116, v116, v117
	v_mul_f32_e32 v117, v105, v105
	v_fmac_f32_e32 v117, v104, v104
	v_cvt_pk_bf16_f32 v108, v108, v109
	v_cvt_pk_bf16_f32 v109, v110, v111
	v_cvt_pk_bf16_f32 v110, v104, v105
	v_mul_f32_e32 v104, v101, v101
	v_mul_f32_e32 v105, v103, v103
	v_fmac_f32_e32 v104, v100, v100
	v_fmac_f32_e32 v105, v102, v102
	v_add_f32_e32 v104, v104, v105
	v_mul_f32_e32 v105, v97, v97
	v_fmac_f32_e32 v105, v96, v96
	v_add_f32_e32 v116, v116, v117
	v_mul_f32_e32 v117, v107, v107
	v_add_f32_e32 v104, v104, v105
	v_mul_f32_e32 v105, v99, v99
	v_fmac_f32_e32 v117, v106, v106
	v_fmac_f32_e32 v105, v98, v98
	v_add_f32_e32 v116, v117, v116
	v_add_f32_e32 v104, v105, v104
	v_add_f32_e32 v104, v116, v104
	v_mov_b32_e32 v105, v104
	s_nop 1
	v_permlane16_swap_b32 v104, v105
	s_mov_b64 s[8:9], 0x8000
	s_waitcnt lgkmcnt(0)
	v_lshl_add_u64 v[114:115], v[142:143], 0, s[8:9]
	v_cvt_pk_bf16_f32 v111, v106, v107
	s_mov_b64 s[8:9], 0x8100
	global_store_dwordx4 v[114:115], v[108:111], off sc0 sc1
	s_nop 1
	v_cvt_pk_bf16_f32 v100, v100, v101
	v_cvt_pk_bf16_f32 v101, v102, v103
	v_cvt_pk_bf16_f32 v102, v96, v97
	v_add_f32_e32 v96, v104, v105
	v_mov_b32_e32 v97, v96
	s_nop 1
	v_permlane32_swap_b32 v96, v97
	v_cvt_pk_bf16_f32 v103, v98, v99
	v_lshl_add_u64 v[98:99], v[142:143], 0, s[8:9]
	global_store_dwordx4 v[98:99], v[100:103], off sc0 sc1
	s_nop 1
	s_and_saveexec_b64 s[8:9], s[0:1]
	s_cbranch_execz .LBB0_2308
	s_waitcnt lgkmcnt(0)
	v_add_f32_e32 v98, v96, v97
	v_or_b32_e32 v96, 16, v144
	v_ashrrev_i32_e32 v97, 31, v96
	v_readlane_b32 s18, v254, 60
	v_lshlrev_b64 v[96:97], 2, v[96:97]
	v_readlane_b32 s19, v254, 61
	s_mul_i32 s14, s48, 0x10c00
	s_nop 0
	v_lshl_add_u64 v[96:97], s[18:19], 0, v[96:97]
	s_mul_i32 s18, s13, 0x43000
	s_ashr_i32 s19, s18, 31
	v_lshl_add_u64 v[96:97], s[18:19], 0, v[96:97]
	v_lshl_add_u64 v[96:97], v[96:97], 0, s[14:15]
	global_store_dword v[96:97], v98, off sc0 sc1
	s_nop 1
.LBB0_2308:
	s_or_b64 exec, exec, s[8:9]
	v_mul_f32_e32 v98, v93, v93
	v_mul_f32_e32 v99, v95, v95
	v_fmac_f32_e32 v98, v92, v92
	v_fmac_f32_e32 v99, v94, v94
	v_add_f32_e32 v98, v98, v99
	v_mul_f32_e32 v99, v89, v89
	v_fmac_f32_e32 v99, v88, v88
	v_cvt_pk_bf16_f32 v92, v92, v93
	v_cvt_pk_bf16_f32 v93, v94, v95
	v_cvt_pk_bf16_f32 v94, v88, v89
	v_mul_f32_e32 v88, v85, v85
	v_mul_f32_e32 v89, v87, v87
	v_fmac_f32_e32 v88, v84, v84
	v_fmac_f32_e32 v89, v86, v86
	v_add_f32_e32 v88, v88, v89
	v_mul_f32_e32 v89, v81, v81
	v_fmac_f32_e32 v89, v80, v80
	v_add_f32_e32 v98, v98, v99
	v_mul_f32_e32 v99, v91, v91
	v_add_f32_e32 v88, v88, v89
	v_mul_f32_e32 v89, v83, v83
	v_fmac_f32_e32 v99, v90, v90
	v_fmac_f32_e32 v89, v82, v82
	v_add_f32_e32 v98, v99, v98
	v_add_f32_e32 v88, v89, v88
	v_add_f32_e32 v88, v98, v88
	v_mov_b32_e32 v89, v88
	s_nop 1
	v_permlane16_swap_b32 v88, v89
	s_mov_b64 s[8:9], 0x10000
	s_waitcnt lgkmcnt(0)
	v_lshl_add_u64 v[96:97], v[142:143], 0, s[8:9]
	v_cvt_pk_bf16_f32 v95, v90, v91
	s_mov_b64 s[8:9], 0x10100
	global_store_dwordx4 v[96:97], v[92:95], off sc0 sc1
	s_nop 1
	v_cvt_pk_bf16_f32 v84, v84, v85
	v_cvt_pk_bf16_f32 v85, v86, v87
	v_cvt_pk_bf16_f32 v86, v80, v81
	v_add_f32_e32 v80, v88, v89
	v_mov_b32_e32 v81, v80
	s_nop 1
	v_permlane32_swap_b32 v80, v81
	v_cvt_pk_bf16_f32 v87, v82, v83
	v_lshl_add_u64 v[82:83], v[142:143], 0, s[8:9]
	global_store_dwordx4 v[82:83], v[84:87], off sc0 sc1
	s_nop 1
	s_and_saveexec_b64 s[8:9], s[0:1]
	s_cbranch_execz .LBB0_2310
	s_waitcnt lgkmcnt(0)
	v_add_f32_e32 v82, v80, v81
	v_or_b32_e32 v80, 32, v144
	v_ashrrev_i32_e32 v81, 31, v80
	v_readlane_b32 s18, v254, 60
	v_lshlrev_b64 v[80:81], 2, v[80:81]
	v_readlane_b32 s19, v254, 61
	s_mul_i32 s14, s48, 0x10c00
	s_nop 0
	v_lshl_add_u64 v[80:81], s[18:19], 0, v[80:81]
	s_mul_i32 s18, s13, 0x43000
	s_ashr_i32 s19, s18, 31
	v_lshl_add_u64 v[80:81], s[18:19], 0, v[80:81]
	v_lshl_add_u64 v[80:81], v[80:81], 0, s[14:15]
	global_store_dword v[80:81], v82, off sc0 sc1
	s_nop 1
.LBB0_2310:
	s_or_b64 exec, exec, s[8:9]
	v_mul_f32_e32 v82, v77, v77
	v_mul_f32_e32 v83, v79, v79
	v_fmac_f32_e32 v82, v76, v76
	v_fmac_f32_e32 v83, v78, v78
	v_add_f32_e32 v82, v82, v83
	v_mul_f32_e32 v83, v73, v73
	v_fmac_f32_e32 v83, v72, v72
	v_cvt_pk_bf16_f32 v76, v76, v77
	v_cvt_pk_bf16_f32 v77, v78, v79
	v_cvt_pk_bf16_f32 v78, v72, v73
	v_mul_f32_e32 v72, v69, v69
	v_mul_f32_e32 v73, v71, v71
	v_fmac_f32_e32 v72, v68, v68
	v_fmac_f32_e32 v73, v70, v70
	v_add_f32_e32 v72, v72, v73
	v_mul_f32_e32 v73, v65, v65
	v_fmac_f32_e32 v73, v64, v64
	v_add_f32_e32 v82, v82, v83
	v_mul_f32_e32 v83, v75, v75
	v_add_f32_e32 v72, v72, v73
	v_mul_f32_e32 v73, v67, v67
	v_fmac_f32_e32 v83, v74, v74
	v_fmac_f32_e32 v73, v66, v66
	v_add_f32_e32 v82, v83, v82
	v_add_f32_e32 v72, v73, v72
	v_add_f32_e32 v72, v82, v72
	v_mov_b32_e32 v73, v72
	s_nop 1
	v_permlane16_swap_b32 v72, v73
	s_mov_b64 s[8:9], 0x18000
	s_waitcnt lgkmcnt(0)
	v_lshl_add_u64 v[80:81], v[142:143], 0, s[8:9]
	v_cvt_pk_bf16_f32 v79, v74, v75
	s_mov_b64 s[8:9], 0x18100
	global_store_dwordx4 v[80:81], v[76:79], off sc0 sc1
	s_nop 1
	v_cvt_pk_bf16_f32 v68, v68, v69
	v_cvt_pk_bf16_f32 v69, v70, v71
	v_cvt_pk_bf16_f32 v70, v64, v65
	v_add_f32_e32 v64, v72, v73
	v_mov_b32_e32 v65, v64
	s_nop 1
	v_permlane32_swap_b32 v64, v65
	v_cvt_pk_bf16_f32 v71, v66, v67
	v_lshl_add_u64 v[66:67], v[142:143], 0, s[8:9]
	global_store_dwordx4 v[66:67], v[68:71], off sc0 sc1
	s_nop 1
	s_and_saveexec_b64 s[8:9], s[0:1]
	s_cbranch_execz .LBB0_2312
	s_waitcnt lgkmcnt(0)
	v_add_f32_e32 v66, v64, v65
	v_or_b32_e32 v64, 48, v144
	v_ashrrev_i32_e32 v65, 31, v64
	v_readlane_b32 s18, v254, 60
	v_lshlrev_b64 v[64:65], 2, v[64:65]
	v_readlane_b32 s19, v254, 61
	s_mul_i32 s14, s48, 0x10c00
	s_nop 0
	v_lshl_add_u64 v[64:65], s[18:19], 0, v[64:65]
	s_mul_i32 s18, s13, 0x43000
	s_ashr_i32 s19, s18, 31
	v_lshl_add_u64 v[64:65], s[18:19], 0, v[64:65]
	v_lshl_add_u64 v[64:65], v[64:65], 0, s[14:15]
	global_store_dword v[64:65], v66, off sc0 sc1
	s_nop 1
.LBB0_2312:
	s_or_b64 exec, exec, s[8:9]
	v_mul_f32_e32 v66, v61, v61
	v_mul_f32_e32 v67, v63, v63
	v_fmac_f32_e32 v66, v60, v60
	v_fmac_f32_e32 v67, v62, v62
	v_add_f32_e32 v66, v66, v67
	v_mul_f32_e32 v67, v57, v57
	v_fmac_f32_e32 v67, v56, v56
	v_cvt_pk_bf16_f32 v60, v60, v61
	v_cvt_pk_bf16_f32 v61, v62, v63
	v_cvt_pk_bf16_f32 v62, v56, v57
	v_mul_f32_e32 v56, v53, v53
	v_mul_f32_e32 v57, v55, v55
	v_fmac_f32_e32 v56, v52, v52
	v_fmac_f32_e32 v57, v54, v54
	v_add_f32_e32 v56, v56, v57
	v_mul_f32_e32 v57, v49, v49
	v_fmac_f32_e32 v57, v48, v48
	v_add_f32_e32 v66, v66, v67
	v_mul_f32_e32 v67, v59, v59
	v_add_f32_e32 v56, v56, v57
	v_mul_f32_e32 v57, v51, v51
	v_fmac_f32_e32 v67, v58, v58
	v_fmac_f32_e32 v57, v50, v50
	v_add_f32_e32 v66, v67, v66
	v_add_f32_e32 v56, v57, v56
	v_add_f32_e32 v56, v66, v56
	v_mov_b32_e32 v57, v56
	s_nop 1
	v_permlane16_swap_b32 v56, v57
	s_mov_b64 s[8:9], 0x40000
	s_waitcnt lgkmcnt(0)
	v_lshl_add_u64 v[64:65], v[142:143], 0, s[8:9]
	v_cvt_pk_bf16_f32 v63, v58, v59
	s_mov_b64 s[8:9], 0x40100
	global_store_dwordx4 v[64:65], v[60:63], off sc0 sc1
	s_nop 1
	v_cvt_pk_bf16_f32 v52, v52, v53
	v_cvt_pk_bf16_f32 v53, v54, v55
	v_cvt_pk_bf16_f32 v54, v48, v49
	v_add_f32_e32 v48, v56, v57
	v_mov_b32_e32 v49, v48
	s_nop 1
	v_permlane32_swap_b32 v48, v49
	v_cvt_pk_bf16_f32 v55, v50, v51
	v_lshl_add_u64 v[50:51], v[142:143], 0, s[8:9]
	global_store_dwordx4 v[50:51], v[52:55], off sc0 sc1
	s_nop 1
	s_and_saveexec_b64 s[8:9], s[0:1]
	s_cbranch_execz .LBB0_2314
	s_mul_i32 s18, s13, 0x43000
	s_ashr_i32 s19, s18, 31
	s_waitcnt lgkmcnt(0)
	v_add_f32_e32 v50, v48, v49
	v_lshl_add_u64 v[48:49], s[18:19], 0, v[112:113]
	s_mul_i32 s14, s48, 0x10c00
	v_lshl_add_u64 v[48:49], v[48:49], 0, s[14:15]
	s_mov_b64 s[18:19], 0x200
	v_lshl_add_u64 v[48:49], v[48:49], 0, s[18:19]
	global_store_dword v[48:49], v50, off sc0 sc1
	s_nop 1
.LBB0_2314:
	s_or_b64 exec, exec, s[8:9]
	v_mul_f32_e32 v50, v45, v45
	v_mul_f32_e32 v51, v47, v47
	v_fmac_f32_e32 v50, v44, v44
	v_fmac_f32_e32 v51, v46, v46
	v_add_f32_e32 v50, v50, v51
	v_mul_f32_e32 v51, v41, v41
	v_fmac_f32_e32 v51, v40, v40
	v_cvt_pk_bf16_f32 v44, v44, v45
	v_cvt_pk_bf16_f32 v45, v46, v47
	v_cvt_pk_bf16_f32 v46, v40, v41
	v_mul_f32_e32 v40, v37, v37
	v_mul_f32_e32 v41, v39, v39
	v_fmac_f32_e32 v40, v36, v36
	v_fmac_f32_e32 v41, v38, v38
	v_add_f32_e32 v40, v40, v41
	v_mul_f32_e32 v41, v33, v33
	v_fmac_f32_e32 v41, v32, v32
	v_add_f32_e32 v50, v50, v51
	v_mul_f32_e32 v51, v43, v43
	v_add_f32_e32 v40, v40, v41
	v_mul_f32_e32 v41, v35, v35
	v_fmac_f32_e32 v51, v42, v42
	v_fmac_f32_e32 v41, v34, v34
	v_add_f32_e32 v50, v51, v50
	v_add_f32_e32 v40, v41, v40
	v_add_f32_e32 v40, v50, v40
	v_mov_b32_e32 v41, v40
	s_nop 1
	v_permlane16_swap_b32 v40, v41
	s_mov_b64 s[8:9], 0x48000
	s_waitcnt lgkmcnt(0)
	v_lshl_add_u64 v[48:49], v[142:143], 0, s[8:9]
	v_cvt_pk_bf16_f32 v47, v42, v43
	s_mov_b64 s[8:9], 0x48100
	global_store_dwordx4 v[48:49], v[44:47], off sc0 sc1
	s_nop 1
	v_cvt_pk_bf16_f32 v36, v36, v37
	v_cvt_pk_bf16_f32 v37, v38, v39
	v_cvt_pk_bf16_f32 v38, v32, v33
	v_add_f32_e32 v32, v40, v41
	v_mov_b32_e32 v33, v32
	s_nop 1
	v_permlane32_swap_b32 v32, v33
	v_cvt_pk_bf16_f32 v39, v34, v35
	v_lshl_add_u64 v[34:35], v[142:143], 0, s[8:9]
	global_store_dwordx4 v[34:35], v[36:39], off sc0 sc1
	s_nop 1
	s_and_saveexec_b64 s[8:9], s[0:1]
	s_cbranch_execz .LBB0_2316
	s_mul_i32 s18, s13, 0x43000
	s_ashr_i32 s19, s18, 31
	s_waitcnt lgkmcnt(0)
	v_add_f32_e32 v34, v32, v33
	v_lshl_add_u64 v[32:33], s[18:19], 0, v[112:113]
	s_mul_i32 s14, s48, 0x10c00
	v_lshl_add_u64 v[32:33], v[32:33], 0, s[14:15]
	s_mov_b64 s[18:19], 0x240
	v_lshl_add_u64 v[32:33], v[32:33], 0, s[18:19]
	global_store_dword v[32:33], v34, off sc0 sc1
	s_nop 1
.LBB0_2316:
	s_or_b64 exec, exec, s[8:9]
	v_mul_f32_e32 v34, v29, v29
	v_mul_f32_e32 v35, v31, v31
	v_fmac_f32_e32 v34, v28, v28
	v_fmac_f32_e32 v35, v30, v30
	v_add_f32_e32 v34, v34, v35
	v_mul_f32_e32 v35, v25, v25
	v_fmac_f32_e32 v35, v24, v24
	v_cvt_pk_bf16_f32 v28, v28, v29
	v_cvt_pk_bf16_f32 v29, v30, v31
	v_cvt_pk_bf16_f32 v30, v24, v25
	v_mul_f32_e32 v24, v21, v21
	v_mul_f32_e32 v25, v23, v23
	v_fmac_f32_e32 v24, v20, v20
	v_fmac_f32_e32 v25, v22, v22
	v_add_f32_e32 v24, v24, v25
	v_mul_f32_e32 v25, v17, v17
	v_fmac_f32_e32 v25, v16, v16
	v_add_f32_e32 v34, v34, v35
	v_mul_f32_e32 v35, v27, v27
	v_add_f32_e32 v24, v24, v25
	v_mul_f32_e32 v25, v19, v19
	v_fmac_f32_e32 v35, v26, v26
	v_fmac_f32_e32 v25, v18, v18
	v_add_f32_e32 v34, v35, v34
	v_add_f32_e32 v24, v25, v24
	v_add_f32_e32 v24, v34, v24
	v_mov_b32_e32 v25, v24
	s_nop 1
	v_permlane16_swap_b32 v24, v25
	s_mov_b64 s[8:9], 0x50000
	s_waitcnt lgkmcnt(0)
	v_lshl_add_u64 v[32:33], v[142:143], 0, s[8:9]
	v_cvt_pk_bf16_f32 v31, v26, v27
	s_mov_b64 s[8:9], 0x50100
	global_store_dwordx4 v[32:33], v[28:31], off sc0 sc1
	s_nop 1
	v_cvt_pk_bf16_f32 v20, v20, v21
	v_cvt_pk_bf16_f32 v21, v22, v23
	v_cvt_pk_bf16_f32 v22, v16, v17
	v_add_f32_e32 v16, v24, v25
	v_mov_b32_e32 v17, v16
	s_nop 1
	v_permlane32_swap_b32 v16, v17
	v_cvt_pk_bf16_f32 v23, v18, v19
	v_lshl_add_u64 v[18:19], v[142:143], 0, s[8:9]
	global_store_dwordx4 v[18:19], v[20:23], off sc0 sc1
	s_nop 1
	s_and_saveexec_b64 s[8:9], s[0:1]
	s_cbranch_execz .LBB0_2318
	s_mul_i32 s18, s13, 0x43000
	s_ashr_i32 s19, s18, 31
	s_waitcnt lgkmcnt(0)
	v_add_f32_e32 v18, v16, v17
	v_lshl_add_u64 v[16:17], s[18:19], 0, v[112:113]
	s_mul_i32 s14, s48, 0x10c00
	v_lshl_add_u64 v[16:17], v[16:17], 0, s[14:15]
	s_mov_b64 s[18:19], 0x280
	v_lshl_add_u64 v[16:17], v[16:17], 0, s[18:19]
	global_store_dword v[16:17], v18, off sc0 sc1
	s_nop 1
.LBB0_2318:
	s_or_b64 exec, exec, s[8:9]
	v_mul_f32_e32 v18, v13, v13
	v_mul_f32_e32 v19, v15, v15
	v_fmac_f32_e32 v18, v12, v12
	v_fmac_f32_e32 v19, v14, v14
	v_add_f32_e32 v18, v18, v19
	v_mul_f32_e32 v19, v9, v9
	v_fmac_f32_e32 v19, v8, v8
	v_cvt_pk_bf16_f32 v12, v12, v13
	v_cvt_pk_bf16_f32 v13, v14, v15
	v_cvt_pk_bf16_f32 v14, v8, v9
	v_mul_f32_e32 v8, v5, v5
	v_mul_f32_e32 v9, v7, v7
	v_fmac_f32_e32 v8, v4, v4
	v_fmac_f32_e32 v9, v6, v6
	v_add_f32_e32 v8, v8, v9
	v_mul_f32_e32 v9, v1, v1
	v_fmac_f32_e32 v9, v0, v0
	v_add_f32_e32 v18, v18, v19
	v_mul_f32_e32 v19, v11, v11
	v_add_f32_e32 v8, v8, v9
	v_mul_f32_e32 v9, v3, v3
	v_fmac_f32_e32 v19, v10, v10
	v_fmac_f32_e32 v9, v2, v2
	v_add_f32_e32 v18, v19, v18
	v_add_f32_e32 v8, v9, v8
	v_add_f32_e32 v8, v18, v8
	v_mov_b32_e32 v9, v8
	s_nop 1
	v_permlane16_swap_b32 v8, v9
	s_waitcnt lgkmcnt(0)
	v_lshl_add_u64 v[16:17], v[142:143], 0, s[50:51]
	v_cvt_pk_bf16_f32 v15, v10, v11
	s_nop 0
	global_store_dwordx4 v[16:17], v[12:15], off sc0 sc1
	s_nop 1
	v_cvt_pk_bf16_f32 v4, v4, v5
	v_cvt_pk_bf16_f32 v5, v6, v7
	v_cvt_pk_bf16_f32 v6, v0, v1
	v_add_f32_e32 v0, v8, v9
	v_mov_b32_e32 v1, v0
	s_nop 1
	v_permlane32_swap_b32 v0, v1
	v_cvt_pk_bf16_f32 v7, v2, v3
	v_lshl_add_u64 v[2:3], v[142:143], 0, s[52:53]
	global_store_dwordx4 v[2:3], v[4:7], off sc0 sc1
	s_nop 1
	s_and_saveexec_b64 s[8:9], s[0:1]
	s_cbranch_execz .LBB0_2320
	s_mul_i32 s18, s13, 0x43000
	s_ashr_i32 s19, s18, 31
	s_waitcnt lgkmcnt(0)
	v_add_f32_e32 v2, v0, v1
	v_lshl_add_u64 v[0:1], s[18:19], 0, v[112:113]
	s_mul_i32 s14, s48, 0x10c00
	v_lshl_add_u64 v[0:1], v[0:1], 0, s[14:15]
	v_lshl_add_u64 v[0:1], v[0:1], 0, s[54:55]
	global_store_dword v[0:1], v2, off sc0 sc1
	s_nop 1
